# baseline (speedup 1.0000x reference)
; #define PG8_STAGE(bufoff, gbase, voff) do { _Pragma("unroll") for (int _i = 0; _i < 2; ++_i) \
;         __builtin_amdgcn_global_load_lds((const unsigned*)((const char*)(gbase) + (voff)[_i]), (LAS unsigned*)(lds + (bufoff) + ldsw + _i * 8192), 16, 0, 0); } while (0)
; #define PG8_LDA(dst, b, h) do { _Pragma("unroll") for (int m = 0; m < 4; ++m) _Pragma("unroll") for (int k = 0; k < 2; ++k) dst[m][k] = *(const LAS bf16x8*)(lds + PG8_SA(b, h) + aoff + m * 2048 + k * 1024); } while (0)
; #define PG8_LDB(dst, b, h) do { _Pragma("unroll") for (int n = 0; n < 2; ++n) _Pragma("unroll") for (int k = 0; k < 2; ++k) dst[n][k] = *(const LAS bf16x8*)(lds + PG8_SB(b, h) + boff + n * 2048 + k * 1024); } while (0)
; #define PG8_MMA(ai, bj, At, Bt) do { __builtin_amdgcn_s_setprio(1); _Pragma("unroll") for (int m = 0; m < 4; ++m) _Pragma("unroll") for (int n = 0; n < 2; ++n) _Pragma("unroll") for (int k = 0; k < 2; ++k) \
;         acc[ai][bj][m][n] = __builtin_amdgcn_mfma_f32_16x16x32_bf16(Bt[n][k], At[m][k], acc[ai][bj][m][n], 0, 0, 0); __builtin_amdgcn_s_setprio(0); } while (0)
; #define PG8_WAIT_V(n) asm volatile("s_waitcnt vmcnt(" #n ")" ::: "memory")
; #define PG8_WAIT_L(n) asm volatile("s_waitcnt lgkmcnt(" #n ")" ::: "memory")
; #define PG8_BAR __builtin_amdgcn_s_barrier()
; #define PG8_SCHED __builtin_amdgcn_sched_barrier(0)
; template <class Epi, class Sched>
; __device__ __forceinline__ void gemm_phase(LAS unsigned char* lds, const Gemm g, const Sched& S, const Epi& E) {
;     ...
;         for (int t = 0; t < nt; t += 2) {
;             const bool last = (t == nt - 2);
;             const char* a1 = cA + (size_t)(t + 1) * kstep;
;             const char* a2 = last ? nA : cA + (size_t)(t + 2) * kstep; const char* b2 = last ? nB : cB + (size_t)(t + 2) * kstep;
;             const char* a3 = a2 + kstep; const char* b3 = b2 + kstep;
;             PG8_LDB(B0, 0, 0); PG8_LDB(B1, 0, 1); PG8_SCHED; PG8_LDA(At, 0, 0); PG8_STAGE(PG8_SA(1, 1), a1 + hstep, voffA);
;             PG8_WAIT_V(8); PG8_WAIT_L(0); PG8_BAR; PG8_MMA(0, 0, At, B0); PG8_MMA(0, 1, At, B1); PG8_BAR; PG8_SCHED;
;             PG8_LDA(At, 0, 1); PG8_STAGE(PG8_SB(0, 0), b2, voffB); PG8_STAGE(PG8_SB(0, 1), b2 + hstep, voffB); PG8_STAGE(PG8_SA(0, 0), a2, voffA);
.LBB0_110:
	ds_read_b128 v[142:145], v169
	ds_read_b128 v[146:149], v169 offset:1024
	ds_read_b128 v[172:175], v169 offset:2048
	ds_read_b128 v[176:179], v169 offset:3072
	ds_read_b128 v[180:183], v170
	ds_read_b128 v[184:187], v170 offset:1024
	ds_read_b128 v[188:191], v170 offset:2048
	ds_read_b128 v[192:195], v170 offset:3072
	s_add_u32 s24, s22, 0xfff80080
	s_addc_u32 s25, s23, -1
	s_cmp_eq_u32 s88, 28
	s_cselect_b32 s27, s3, s25
	s_cselect_b32 s26, s14, s24
	s_cselect_b32 s25, s13, s33
	s_cselect_b32 s24, s15, s17
	v_lshl_add_u64 v[238:239], s[22:23], 0, v[132:133]
	s_add_i32 m0, s30, 0xc000
	ds_read_b128 v[196:199], v171
	ds_read_b128 v[202:205], v171 offset:1024
	ds_read_b128 v[206:209], v171 offset:2048
	ds_read_b128 v[210:213], v171 offset:3072
	ds_read_b128 v[214:217], v171 offset:4096
	ds_read_b128 v[226:229], v171 offset:5120
	ds_read_b128 v[230:233], v171 offset:6144
	ds_read_b128 v[234:237], v171 offset:7168
	global_load_lds_dwordx4 v[238:239], off
	v_lshl_add_u64 v[238:239], s[22:23], 0, v[134:135]
	s_add_i32 m0, s30, 0xe000
	s_nop 0
	global_load_lds_dwordx4 v[238:239], off
	s_waitcnt vmcnt(8)
	s_waitcnt lgkmcnt(0)
	s_barrier
	s_setprio 1
	s_waitcnt lgkmcnt(0)
	v_mfma_f32_16x16x32_bf16 v[124:127], v[142:145], v[196:199], v[124:127]
	v_mfma_f32_16x16x32_bf16 v[120:123], v[172:175], v[196:199], v[120:123]
	v_mfma_f32_16x16x32_bf16 v[116:119], v[142:145], v[206:209], v[116:119]
	v_mfma_f32_16x16x32_bf16 v[112:115], v[172:175], v[206:209], v[112:115]
	v_mfma_f32_16x16x32_bf16 v[108:111], v[142:145], v[214:217], v[108:111]
	v_mfma_f32_16x16x32_bf16 v[104:107], v[172:175], v[214:217], v[104:107]
	v_mfma_f32_16x16x32_bf16 v[100:103], v[142:145], v[230:233], v[100:103]
	v_mfma_f32_16x16x32_bf16 v[96:99], v[172:175], v[230:233], v[96:99]
	v_mfma_f32_16x16x32_bf16 v[124:127], v[146:149], v[202:205], v[124:127]
	v_mfma_f32_16x16x32_bf16 v[120:123], v[176:179], v[202:205], v[120:123]
	v_mfma_f32_16x16x32_bf16 v[116:119], v[146:149], v[210:213], v[116:119]
	v_mfma_f32_16x16x32_bf16 v[112:115], v[176:179], v[210:213], v[112:115]
	v_mfma_f32_16x16x32_bf16 v[108:111], v[146:149], v[226:229], v[108:111]
	v_mfma_f32_16x16x32_bf16 v[104:107], v[176:179], v[226:229], v[104:107]
	v_mfma_f32_16x16x32_bf16 v[100:103], v[146:149], v[234:237], v[100:103]
	v_mfma_f32_16x16x32_bf16 v[96:99], v[176:179], v[234:237], v[96:99]
	v_mfma_f32_16x16x32_bf16 v[60:63], v[180:183], v[196:199], v[60:63]
	v_mfma_f32_16x16x32_bf16 v[56:59], v[188:191], v[196:199], v[56:59]
	v_mfma_f32_16x16x32_bf16 v[52:55], v[180:183], v[206:209], v[52:55]
	v_mfma_f32_16x16x32_bf16 v[48:51], v[188:191], v[206:209], v[48:51]
	v_mfma_f32_16x16x32_bf16 v[44:47], v[180:183], v[214:217], v[44:47]
	v_mfma_f32_16x16x32_bf16 v[40:43], v[188:191], v[214:217], v[40:43]
	v_mfma_f32_16x16x32_bf16 v[36:39], v[180:183], v[230:233], v[36:39]
	v_mfma_f32_16x16x32_bf16 v[32:35], v[188:191], v[230:233], v[32:35]
	v_mfma_f32_16x16x32_bf16 v[60:63], v[184:187], v[202:205], v[60:63]
	v_mfma_f32_16x16x32_bf16 v[56:59], v[192:195], v[202:205], v[56:59]
	v_mfma_f32_16x16x32_bf16 v[52:55], v[184:187], v[210:213], v[52:55]
	v_mfma_f32_16x16x32_bf16 v[48:51], v[192:195], v[210:213], v[48:51]
	v_mfma_f32_16x16x32_bf16 v[44:47], v[184:187], v[226:229], v[44:47]
	v_mfma_f32_16x16x32_bf16 v[40:43], v[192:195], v[226:229], v[40:43]
	v_mfma_f32_16x16x32_bf16 v[36:39], v[184:187], v[234:237], v[36:39]
	v_mfma_f32_16x16x32_bf16 v[32:35], v[192:195], v[234:237], v[32:35]
	s_setprio 0
	s_barrier
	s_add_i32 s89, s46, s28
	v_lshl_add_u64 v[238:239], s[24:25], 0, v[156:157]
	s_mov_b32 m0, s89
	ds_read_b128 v[196:199], v171 offset:16384
	ds_read_b128 v[202:205], v171 offset:17408
	ds_read_b128 v[206:209], v171 offset:18432
	ds_read_b128 v[210:213], v171 offset:19456
	ds_read_b128 v[214:217], v171 offset:20480
	ds_read_b128 v[226:229], v171 offset:21504
	ds_read_b128 v[230:233], v171 offset:22528
	ds_read_b128 v[234:237], v171 offset:23552
	global_load_lds_dwordx4 v[238:239], off
	s_add_i32 m0, s89, 0x2000
	s_add_u32 s90, s24, 0x80000
	v_lshl_add_u64 v[240:241], s[24:25], 0, v[160:161]
	s_addc_u32 s91, s25, 0
	s_add_i32 s89, s47, s28
	global_load_lds_dwordx4 v[240:241], off
	v_lshl_add_u64 v[242:243], s[90:91], 0, v[156:157]
	s_mov_b32 m0, s89
	v_lshl_add_u64 v[244:245], s[26:27], 0, v[158:159]
	global_load_lds_dwordx4 v[242:243], off
	v_lshl_add_u64 v[242:243], s[90:91], 0, v[160:161]
	s_add_i32 m0, s89, 0x2000
	s_nop 0
	global_load_lds_dwordx4 v[242:243], off
	v_lshl_add_u64 v[242:243], s[26:27], 0, v[154:155]
	s_mov_b32 m0, s30
	s_nop 0
	global_load_lds_dwordx4 v[242:243], off
	s_mov_b32 m0, s31
	s_nop 0
	global_load_lds_dwordx4 v[244:245], off
	s_waitcnt vmcnt(8)
	s_waitcnt lgkmcnt(0)
	s_barrier
; #define PG8_STAGE(bufoff, gbase, voff) do { _Pragma("unroll") for (int _i = 0; _i < 2; ++_i) \
;         __builtin_amdgcn_global_load_lds((const unsigned*)((const char*)(gbase) + (voff)[_i]), (LAS unsigned*)(lds + (bufoff) + ldsw + _i * 8192), 16, 0, 0); } while (0)
; #define PG8_LDA(dst, b, h) do { _Pragma("unroll") for (int m = 0; m < 4; ++m) _Pragma("unroll") for (int k = 0; k < 2; ++k) dst[m][k] = *(const LAS bf16x8*)(lds + PG8_SA(b, h) + aoff + m * 2048 + k * 1024); } while (0)
; #define PG8_LDB(dst, b, h) do { _Pragma("unroll") for (int n = 0; n < 2; ++n) _Pragma("unroll") for (int k = 0; k < 2; ++k) dst[n][k] = *(const LAS bf16x8*)(lds + PG8_SB(b, h) + boff + n * 2048 + k * 1024); } while (0)
; #define PG8_MMA(ai, bj, At, Bt) do { __builtin_amdgcn_s_setprio(1); _Pragma("unroll") for (int m = 0; m < 4; ++m) _Pragma("unroll") for (int n = 0; n < 2; ++n) _Pragma("unroll") for (int k = 0; k < 2; ++k) \
;         acc[ai][bj][m][n] = __builtin_amdgcn_mfma_f32_16x16x32_bf16(Bt[n][k], At[m][k], acc[ai][bj][m][n], 0, 0, 0); __builtin_amdgcn_s_setprio(0); } while (0)
; #define PG8_WAIT_V(n) asm volatile("s_waitcnt vmcnt(" #n ")" ::: "memory")
; #define PG8_WAIT_L(n) asm volatile("s_waitcnt lgkmcnt(" #n ")" ::: "memory")
; #define PG8_BAR __builtin_amdgcn_s_barrier()
; #define PG8_SCHED __builtin_amdgcn_sched_barrier(0)
; template <class Epi, class Sched>
; __device__ __forceinline__ void gemm_phase(LAS unsigned char* lds, const Gemm g, const Sched& S, const Epi& E) {
;     ...
;             PG8_WAIT_V(8); PG8_WAIT_L(0); PG8_BAR; PG8_MMA(1, 0, At, B0); PG8_MMA(1, 1, At, B1); PG8_BAR; PG8_SCHED;
;             PG8_LDB(B0, 1, 0); PG8_LDB(B1, 1, 1); PG8_SCHED; PG8_LDA(At, 1, 0); PG8_STAGE(PG8_SA(0, 1), a2 + hstep, voffA);
;             PG8_WAIT_V(8); PG8_WAIT_L(0); PG8_BAR; PG8_MMA(0, 0, At, B0); PG8_MMA(0, 1, At, B1); PG8_BAR; PG8_SCHED;
	s_setprio 1
	s_waitcnt lgkmcnt(0)
	v_mfma_f32_16x16x32_bf16 v[92:95], v[142:145], v[196:199], v[92:95]
	v_mfma_f32_16x16x32_bf16 v[88:91], v[172:175], v[196:199], v[88:91]
	v_mfma_f32_16x16x32_bf16 v[84:87], v[142:145], v[206:209], v[84:87]
	v_mfma_f32_16x16x32_bf16 v[80:83], v[172:175], v[206:209], v[80:83]
	v_mfma_f32_16x16x32_bf16 v[76:79], v[142:145], v[214:217], v[76:79]
	v_mfma_f32_16x16x32_bf16 v[72:75], v[172:175], v[214:217], v[72:75]
	v_mfma_f32_16x16x32_bf16 v[68:71], v[142:145], v[230:233], v[68:71]
	v_mfma_f32_16x16x32_bf16 v[64:67], v[172:175], v[230:233], v[64:67]
	v_mfma_f32_16x16x32_bf16 v[92:95], v[146:149], v[202:205], v[92:95]
	v_mfma_f32_16x16x32_bf16 v[88:91], v[176:179], v[202:205], v[88:91]
	v_mfma_f32_16x16x32_bf16 v[84:87], v[146:149], v[210:213], v[84:87]
	v_mfma_f32_16x16x32_bf16 v[80:83], v[176:179], v[210:213], v[80:83]
	v_mfma_f32_16x16x32_bf16 v[76:79], v[146:149], v[226:229], v[76:79]
	v_mfma_f32_16x16x32_bf16 v[72:75], v[176:179], v[226:229], v[72:75]
	v_mfma_f32_16x16x32_bf16 v[68:71], v[146:149], v[234:237], v[68:71]
	v_mfma_f32_16x16x32_bf16 v[64:67], v[176:179], v[234:237], v[64:67]
	v_mfma_f32_16x16x32_bf16 v[28:31], v[180:183], v[196:199], v[28:31]
	v_mfma_f32_16x16x32_bf16 v[24:27], v[188:191], v[196:199], v[24:27]
	v_mfma_f32_16x16x32_bf16 v[20:23], v[180:183], v[206:209], v[20:23]
	v_mfma_f32_16x16x32_bf16 v[16:19], v[188:191], v[206:209], v[16:19]
	v_mfma_f32_16x16x32_bf16 v[12:15], v[180:183], v[214:217], v[12:15]
	v_mfma_f32_16x16x32_bf16 v[8:11], v[188:191], v[214:217], v[8:11]
	v_mfma_f32_16x16x32_bf16 v[4:7], v[180:183], v[230:233], v[4:7]
	v_mfma_f32_16x16x32_bf16 v[0:3], v[188:191], v[230:233], v[0:3]
	v_mfma_f32_16x16x32_bf16 v[28:31], v[184:187], v[202:205], v[28:31]
	v_mfma_f32_16x16x32_bf16 v[24:27], v[192:195], v[202:205], v[24:27]
	v_mfma_f32_16x16x32_bf16 v[20:23], v[184:187], v[210:213], v[20:23]
	v_mfma_f32_16x16x32_bf16 v[16:19], v[192:195], v[210:213], v[16:19]
	v_mfma_f32_16x16x32_bf16 v[12:15], v[184:187], v[226:229], v[12:15]
	v_mfma_f32_16x16x32_bf16 v[8:11], v[192:195], v[226:229], v[8:11]
	v_mfma_f32_16x16x32_bf16 v[4:7], v[184:187], v[234:237], v[4:7]
	v_mfma_f32_16x16x32_bf16 v[0:3], v[192:195], v[234:237], v[0:3]
	s_setprio 0
	s_barrier
	s_add_i32 s89, 0, 0x18000
	v_add_u32_e32 v128, s89, v164
	s_add_i32 s90, 0, 0x1c000
	ds_read_b128 v[142:145], v128
	ds_read_b128 v[146:149], v128 offset:1024
	ds_read_b128 v[172:175], v128 offset:2048
	ds_read_b128 v[176:179], v128 offset:3072
	v_add_u32_e32 v128, s90, v164
	ds_read_b128 v[180:183], v128
	ds_read_b128 v[184:187], v128 offset:1024
	ds_read_b128 v[188:191], v128 offset:2048
	ds_read_b128 v[192:195], v128 offset:3072
	s_add_u32 s26, s26, 0x80000
	s_addc_u32 s27, s27, 0
	s_mov_b32 m0, s34
	v_lshl_add_u64 v[246:247], s[26:27], 0, v[154:155]
	ds_read_b128 v[196:199], v171 offset:32768
	ds_read_b128 v[202:205], v171 offset:33792
	ds_read_b128 v[206:209], v171 offset:34816
	ds_read_b128 v[210:213], v171 offset:35840
	ds_read_b128 v[214:217], v171 offset:36864
	ds_read_b128 v[226:229], v171 offset:37888
	ds_read_b128 v[230:233], v171 offset:38912
	ds_read_b128 v[234:237], v171 offset:39936
	global_load_lds_dwordx4 v[246:247], off
	v_lshl_add_u64 v[246:247], s[26:27], 0, v[158:159]
	s_mov_b32 m0, s35
	s_nop 0
	global_load_lds_dwordx4 v[246:247], off
	s_waitcnt vmcnt(8)
	s_waitcnt lgkmcnt(0)
	s_barrier
	s_setprio 1
	s_waitcnt lgkmcnt(0)
	v_mfma_f32_16x16x32_bf16 v[124:127], v[142:145], v[196:199], v[124:127]
	v_mfma_f32_16x16x32_bf16 v[120:123], v[172:175], v[196:199], v[120:123]
	v_mfma_f32_16x16x32_bf16 v[116:119], v[142:145], v[206:209], v[116:119]
	v_mfma_f32_16x16x32_bf16 v[112:115], v[172:175], v[206:209], v[112:115]
	v_mfma_f32_16x16x32_bf16 v[108:111], v[142:145], v[214:217], v[108:111]
	v_mfma_f32_16x16x32_bf16 v[104:107], v[172:175], v[214:217], v[104:107]
	v_mfma_f32_16x16x32_bf16 v[100:103], v[142:145], v[230:233], v[100:103]
	v_mfma_f32_16x16x32_bf16 v[96:99], v[172:175], v[230:233], v[96:99]
	v_mfma_f32_16x16x32_bf16 v[124:127], v[146:149], v[202:205], v[124:127]
	v_mfma_f32_16x16x32_bf16 v[120:123], v[176:179], v[202:205], v[120:123]
	v_mfma_f32_16x16x32_bf16 v[116:119], v[146:149], v[210:213], v[116:119]
	v_mfma_f32_16x16x32_bf16 v[112:115], v[176:179], v[210:213], v[112:115]
	v_mfma_f32_16x16x32_bf16 v[108:111], v[146:149], v[226:229], v[108:111]
	v_mfma_f32_16x16x32_bf16 v[104:107], v[176:179], v[226:229], v[104:107]
	v_mfma_f32_16x16x32_bf16 v[100:103], v[146:149], v[234:237], v[100:103]
	v_mfma_f32_16x16x32_bf16 v[96:99], v[176:179], v[234:237], v[96:99]
	v_mfma_f32_16x16x32_bf16 v[60:63], v[180:183], v[196:199], v[60:63]
	v_mfma_f32_16x16x32_bf16 v[56:59], v[188:191], v[196:199], v[56:59]
	v_mfma_f32_16x16x32_bf16 v[52:55], v[180:183], v[206:209], v[52:55]
	v_mfma_f32_16x16x32_bf16 v[48:51], v[188:191], v[206:209], v[48:51]
	v_mfma_f32_16x16x32_bf16 v[44:47], v[180:183], v[214:217], v[44:47]
	v_mfma_f32_16x16x32_bf16 v[40:43], v[188:191], v[214:217], v[40:43]
	v_mfma_f32_16x16x32_bf16 v[36:39], v[180:183], v[230:233], v[36:39]
	v_mfma_f32_16x16x32_bf16 v[32:35], v[188:191], v[230:233], v[32:35]
	v_mfma_f32_16x16x32_bf16 v[60:63], v[184:187], v[202:205], v[60:63]
	v_mfma_f32_16x16x32_bf16 v[56:59], v[192:195], v[202:205], v[56:59]
	v_mfma_f32_16x16x32_bf16 v[52:55], v[184:187], v[210:213], v[52:55]
	v_mfma_f32_16x16x32_bf16 v[48:51], v[192:195], v[210:213], v[48:51]
	v_mfma_f32_16x16x32_bf16 v[44:47], v[184:187], v[226:229], v[44:47]
	v_mfma_f32_16x16x32_bf16 v[40:43], v[192:195], v[226:229], v[40:43]
	v_mfma_f32_16x16x32_bf16 v[36:39], v[184:187], v[234:237], v[36:39]
	v_mfma_f32_16x16x32_bf16 v[32:35], v[192:195], v[234:237], v[32:35]
	s_setprio 0
	s_barrier
; #define PG8_STAGE(bufoff, gbase, voff) do { _Pragma("unroll") for (int _i = 0; _i < 2; ++_i) \
;         __builtin_amdgcn_global_load_lds((const unsigned*)((const char*)(gbase) + (voff)[_i]), (LAS unsigned*)(lds + (bufoff) + ldsw + _i * 8192), 16, 0, 0); } while (0)
; #define PG8_LDA(dst, b, h) do { _Pragma("unroll") for (int m = 0; m < 4; ++m) _Pragma("unroll") for (int k = 0; k < 2; ++k) dst[m][k] = *(const LAS bf16x8*)(lds + PG8_SA(b, h) + aoff + m * 2048 + k * 1024); } while (0)
; #define PG8_MMA(ai, bj, At, Bt) do { __builtin_amdgcn_s_setprio(1); _Pragma("unroll") for (int m = 0; m < 4; ++m) _Pragma("unroll") for (int n = 0; n < 2; ++n) _Pragma("unroll") for (int k = 0; k < 2; ++k) \
;         acc[ai][bj][m][n] = __builtin_amdgcn_mfma_f32_16x16x32_bf16(Bt[n][k], At[m][k], acc[ai][bj][m][n], 0, 0, 0); __builtin_amdgcn_s_setprio(0); } while (0)
; #define PG8_WAIT_V(n) asm volatile("s_waitcnt vmcnt(" #n ")" ::: "memory")
; #define PG8_WAIT_L(n) asm volatile("s_waitcnt lgkmcnt(" #n ")" ::: "memory")
; #define PG8_BAR __builtin_amdgcn_s_barrier()
; #define PG8_SCHED __builtin_amdgcn_sched_barrier(0)
; template <class Epi, class Sched>
; __device__ __forceinline__ void gemm_phase(LAS unsigned char* lds, const Gemm g, const Sched& S, const Epi& E) {
;     ...
;             PG8_LDA(At, 1, 1); PG8_STAGE(PG8_SB(1, 0), b3, voffB); PG8_STAGE(PG8_SB(1, 1), b3 + hstep, voffB); PG8_STAGE(PG8_SA(1, 0), a3, voffA);
;             PG8_WAIT_V(8); PG8_WAIT_L(0); PG8_BAR; PG8_MMA(1, 0, At, B0); PG8_MMA(1, 1, At, B1); PG8_BAR; PG8_SCHED;
;         }
	s_add_i32 s26, s89, s28
	v_lshl_add_u64 v[238:239], v[238:239], 0, s[8:9]
	s_mov_b32 m0, s26
	ds_read_b128 v[196:199], v171 offset:49152
	ds_read_b128 v[202:205], v171 offset:50176
	ds_read_b128 v[206:209], v171 offset:51200
	ds_read_b128 v[210:213], v171 offset:52224
	ds_read_b128 v[214:217], v171 offset:53248
	ds_read_b128 v[226:229], v171 offset:54272
	ds_read_b128 v[230:233], v171 offset:55296
	ds_read_b128 v[234:237], v171 offset:56320
	global_load_lds_dwordx4 v[238:239], off
	s_add_i32 m0, s26, 0x2000
	s_add_u32 s24, s24, 0x80080
	v_lshl_add_u64 v[238:239], v[240:241], 0, s[8:9]
	s_addc_u32 s25, s25, 0
	s_add_i32 s26, s90, s28
	global_load_lds_dwordx4 v[238:239], off
	v_lshl_add_u64 v[238:239], s[24:25], 0, v[156:157]
	s_mov_b32 m0, s26
	s_nop 0
	global_load_lds_dwordx4 v[238:239], off
	v_lshl_add_u64 v[238:239], s[24:25], 0, v[160:161]
	s_add_i32 m0, s26, 0x2000
	s_nop 0
	global_load_lds_dwordx4 v[238:239], off
	v_lshl_add_u64 v[238:239], v[242:243], 0, s[8:9]
	s_mov_b32 m0, s36
	s_nop 0
	global_load_lds_dwordx4 v[238:239], off
	v_lshl_add_u64 v[238:239], v[244:245], 0, s[8:9]
	s_mov_b32 m0, s37
	s_nop 0
	global_load_lds_dwordx4 v[238:239], off
	s_waitcnt vmcnt(8)
	s_waitcnt lgkmcnt(0)
	s_barrier
	s_setprio 1
	s_waitcnt lgkmcnt(0)
	v_mfma_f32_16x16x32_bf16 v[92:95], v[142:145], v[196:199], v[92:95]
	v_mfma_f32_16x16x32_bf16 v[88:91], v[172:175], v[196:199], v[88:91]
	v_mfma_f32_16x16x32_bf16 v[84:87], v[142:145], v[206:209], v[84:87]
	v_mfma_f32_16x16x32_bf16 v[80:83], v[172:175], v[206:209], v[80:83]
	v_mfma_f32_16x16x32_bf16 v[76:79], v[142:145], v[214:217], v[76:79]
	v_mfma_f32_16x16x32_bf16 v[72:75], v[172:175], v[214:217], v[72:75]
	v_mfma_f32_16x16x32_bf16 v[68:71], v[142:145], v[230:233], v[68:71]
	v_mfma_f32_16x16x32_bf16 v[64:67], v[172:175], v[230:233], v[64:67]
	v_mfma_f32_16x16x32_bf16 v[92:95], v[146:149], v[202:205], v[92:95]
	v_mfma_f32_16x16x32_bf16 v[88:91], v[176:179], v[202:205], v[88:91]
	v_mfma_f32_16x16x32_bf16 v[84:87], v[146:149], v[210:213], v[84:87]
	v_mfma_f32_16x16x32_bf16 v[80:83], v[176:179], v[210:213], v[80:83]
	v_mfma_f32_16x16x32_bf16 v[76:79], v[146:149], v[226:229], v[76:79]
	v_mfma_f32_16x16x32_bf16 v[72:75], v[176:179], v[226:229], v[72:75]
	v_mfma_f32_16x16x32_bf16 v[68:71], v[146:149], v[234:237], v[68:71]
	v_mfma_f32_16x16x32_bf16 v[64:67], v[176:179], v[234:237], v[64:67]
	v_mfma_f32_16x16x32_bf16 v[28:31], v[180:183], v[196:199], v[28:31]
	v_mfma_f32_16x16x32_bf16 v[24:27], v[188:191], v[196:199], v[24:27]
	v_mfma_f32_16x16x32_bf16 v[20:23], v[180:183], v[206:209], v[20:23]
	v_mfma_f32_16x16x32_bf16 v[16:19], v[188:191], v[206:209], v[16:19]
	v_mfma_f32_16x16x32_bf16 v[12:15], v[180:183], v[214:217], v[12:15]
	v_mfma_f32_16x16x32_bf16 v[8:11], v[188:191], v[214:217], v[8:11]
	v_mfma_f32_16x16x32_bf16 v[4:7], v[180:183], v[230:233], v[4:7]
	v_mfma_f32_16x16x32_bf16 v[0:3], v[188:191], v[230:233], v[0:3]
	v_mfma_f32_16x16x32_bf16 v[28:31], v[184:187], v[202:205], v[28:31]
	v_mfma_f32_16x16x32_bf16 v[24:27], v[192:195], v[202:205], v[24:27]
	v_mfma_f32_16x16x32_bf16 v[20:23], v[184:187], v[210:213], v[20:23]
	v_mfma_f32_16x16x32_bf16 v[16:19], v[192:195], v[210:213], v[16:19]
	v_mfma_f32_16x16x32_bf16 v[12:15], v[184:187], v[226:229], v[12:15]
	v_mfma_f32_16x16x32_bf16 v[8:11], v[192:195], v[226:229], v[8:11]
	v_mfma_f32_16x16x32_bf16 v[4:7], v[184:187], v[234:237], v[4:7]
	v_mfma_f32_16x16x32_bf16 v[0:3], v[192:195], v[234:237], v[0:3]
	s_setprio 0
	s_barrier
	s_add_i32 s88, s88, 2
	s_add_u32 s22, s22, 0x100
	s_addc_u32 s23, s23, 0
	s_add_u32 s17, s17, 0x100
	s_addc_u32 s33, s33, 0
	s_cmp_gt_u32 s88, 29
	s_cbranch_scc0 .LBB0_110
	s_and_b64 vcc, exec, s[10:11]
	s_cbranch_vccz .LBB0_113
	s_barrier

; #define PG8_STAGE(bufoff, gbase, voff) do { _Pragma("unroll") for (int _i = 0; _i < 2; ++_i) \
;         __builtin_amdgcn_global_load_lds((const unsigned*)((const char*)(gbase) + (voff)[_i]), (LAS unsigned*)(lds + (bufoff) + ldsw + _i * 8192), 16, 0, 0); } while (0)
; #define PG8_LDA(dst, b, h) do { _Pragma("unroll") for (int m = 0; m < 4; ++m) _Pragma("unroll") for (int k = 0; k < 2; ++k) dst[m][k] = *(const LAS bf16x8*)(lds + PG8_SA(b, h) + aoff + m * 2048 + k * 1024); } while (0)
; #define PG8_LDB(dst, b, h) do { _Pragma("unroll") for (int n = 0; n < 2; ++n) _Pragma("unroll") for (int k = 0; k < 2; ++k) dst[n][k] = *(const LAS bf16x8*)(lds + PG8_SB(b, h) + boff + n * 2048 + k * 1024); } while (0)
; #define PG8_MMA(ai, bj, At, Bt) do { __builtin_amdgcn_s_setprio(1); _Pragma("unroll") for (int m = 0; m < 4; ++m) _Pragma("unroll") for (int n = 0; n < 2; ++n) _Pragma("unroll") for (int k = 0; k < 2; ++k) \
;         acc[ai][bj][m][n] = __builtin_amdgcn_mfma_f32_16x16x32_bf16(Bt[n][k], At[m][k], acc[ai][bj][m][n], 0, 0, 0); __builtin_amdgcn_s_setprio(0); } while (0)
; #define PG8_WAIT_V(n) asm volatile("s_waitcnt vmcnt(" #n ")" ::: "memory")
; #define PG8_WAIT_L(n) asm volatile("s_waitcnt lgkmcnt(" #n ")" ::: "memory")
; #define PG8_BAR __builtin_amdgcn_s_barrier()
; #define PG8_SCHED __builtin_amdgcn_sched_barrier(0)
; template <class Epi, class Sched>
; __device__ __forceinline__ void gemm_phase(LAS unsigned char* lds, const Gemm g, const Sched& S, const Epi& E) {
;     ...
;         for (int t = 0; t < nt; t += 2) {
;             const bool last = (t == nt - 2);
;             const char* a1 = cA + (size_t)(t + 1) * kstep;
;             const char* a2 = last ? nA : cA + (size_t)(t + 2) * kstep; const char* b2 = last ? nB : cB + (size_t)(t + 2) * kstep;
;             const char* a3 = a2 + kstep; const char* b3 = b2 + kstep;
;             PG8_LDB(B0, 0, 0); PG8_LDB(B1, 0, 1); PG8_SCHED; PG8_LDA(At, 0, 0); PG8_STAGE(PG8_SA(1, 1), a1 + hstep, voffA);
;             PG8_WAIT_V(8); PG8_WAIT_L(0); PG8_BAR; PG8_MMA(0, 0, At, B0); PG8_MMA(0, 1, At, B1); PG8_BAR; PG8_SCHED;
;             PG8_LDA(At, 0, 1); PG8_STAGE(PG8_SB(0, 0), b2, voffB); PG8_STAGE(PG8_SB(0, 1), b2 + hstep, voffB); PG8_STAGE(PG8_SA(0, 0), a2, voffA);
.LBB0_343:
	ds_read_b128 v[170:173], v145
	ds_read_b128 v[174:177], v145 offset:1024
	ds_read_b128 v[178:181], v145 offset:2048
	ds_read_b128 v[182:185], v145 offset:3072
	ds_read_b128 v[186:189], v146
	ds_read_b128 v[190:193], v146 offset:1024
	ds_read_b128 v[194:197], v146 offset:2048
	ds_read_b128 v[204:207], v146 offset:3072
	s_add_u32 s26, s24, 0xfff80080
	s_addc_u32 s27, s25, -1
	s_cmp_eq_u32 s38, 28
	s_cselect_b32 s29, s3, s27
	s_cselect_b32 s28, s14, s26
	s_cselect_b32 s27, s13, s33
	s_cselect_b32 s26, s15, s17
	v_lshl_add_u64 v[142:143], s[24:25], 0, v[128:129]
	s_add_i32 m0, s23, 0xc000
	ds_read_b128 v[208:211], v147
	ds_read_b128 v[212:215], v147 offset:1024
	ds_read_b128 v[226:229], v147 offset:2048
	ds_read_b128 v[230:233], v147 offset:3072
	ds_read_b128 v[234:237], v147 offset:4096
	ds_read_b128 v[238:241], v147 offset:5120
	ds_read_b128 v[242:245], v147 offset:6144
	ds_read_b128 v[246:249], v147 offset:7168
	global_load_lds_dwordx4 v[142:143], off
	v_lshl_add_u64 v[142:143], s[24:25], 0, v[130:131]
	s_add_i32 m0, s23, 0xe000
	s_nop 0
	global_load_lds_dwordx4 v[142:143], off
	s_waitcnt vmcnt(8)
	s_waitcnt lgkmcnt(0)
	s_barrier
	s_setprio 1
	s_waitcnt lgkmcnt(0)
	v_mfma_f32_16x16x32_bf16 v[124:127], v[170:173], v[208:211], v[124:127]
	v_mfma_f32_16x16x32_bf16 v[120:123], v[178:181], v[208:211], v[120:123]
	v_mfma_f32_16x16x32_bf16 v[116:119], v[170:173], v[226:229], v[116:119]
	v_mfma_f32_16x16x32_bf16 v[112:115], v[178:181], v[226:229], v[112:115]
	v_mfma_f32_16x16x32_bf16 v[108:111], v[170:173], v[234:237], v[108:111]
	v_mfma_f32_16x16x32_bf16 v[104:107], v[178:181], v[234:237], v[104:107]
	v_mfma_f32_16x16x32_bf16 v[100:103], v[170:173], v[242:245], v[100:103]
	v_mfma_f32_16x16x32_bf16 v[96:99], v[178:181], v[242:245], v[96:99]
	v_mfma_f32_16x16x32_bf16 v[124:127], v[174:177], v[212:215], v[124:127]
	v_mfma_f32_16x16x32_bf16 v[120:123], v[182:185], v[212:215], v[120:123]
	v_mfma_f32_16x16x32_bf16 v[116:119], v[174:177], v[230:233], v[116:119]
	v_mfma_f32_16x16x32_bf16 v[112:115], v[182:185], v[230:233], v[112:115]
	v_mfma_f32_16x16x32_bf16 v[108:111], v[174:177], v[238:241], v[108:111]
	v_mfma_f32_16x16x32_bf16 v[104:107], v[182:185], v[238:241], v[104:107]
	v_mfma_f32_16x16x32_bf16 v[100:103], v[174:177], v[246:249], v[100:103]
	v_mfma_f32_16x16x32_bf16 v[96:99], v[182:185], v[246:249], v[96:99]
	v_mfma_f32_16x16x32_bf16 v[60:63], v[186:189], v[208:211], v[60:63]
	v_mfma_f32_16x16x32_bf16 v[56:59], v[194:197], v[208:211], v[56:59]
	v_mfma_f32_16x16x32_bf16 v[52:55], v[186:189], v[226:229], v[52:55]
	v_mfma_f32_16x16x32_bf16 v[48:51], v[194:197], v[226:229], v[48:51]
	v_mfma_f32_16x16x32_bf16 v[44:47], v[186:189], v[234:237], v[44:47]
	v_mfma_f32_16x16x32_bf16 v[40:43], v[194:197], v[234:237], v[40:43]
	v_mfma_f32_16x16x32_bf16 v[36:39], v[186:189], v[242:245], v[36:39]
	v_mfma_f32_16x16x32_bf16 v[32:35], v[194:197], v[242:245], v[32:35]
	v_mfma_f32_16x16x32_bf16 v[60:63], v[190:193], v[212:215], v[60:63]
	v_mfma_f32_16x16x32_bf16 v[56:59], v[204:207], v[212:215], v[56:59]
	v_mfma_f32_16x16x32_bf16 v[52:55], v[190:193], v[230:233], v[52:55]
	v_mfma_f32_16x16x32_bf16 v[48:51], v[204:207], v[230:233], v[48:51]
	v_mfma_f32_16x16x32_bf16 v[44:47], v[190:193], v[238:241], v[44:47]
	v_mfma_f32_16x16x32_bf16 v[40:43], v[204:207], v[238:241], v[40:43]
	v_mfma_f32_16x16x32_bf16 v[36:39], v[190:193], v[246:249], v[36:39]
	v_mfma_f32_16x16x32_bf16 v[32:35], v[204:207], v[246:249], v[32:35]
	s_setprio 0
	s_barrier
	s_add_i32 s39, s64, s36
	v_lshl_add_u64 v[142:143], s[26:27], 0, v[156:157]
	s_mov_b32 m0, s39
	ds_read_b128 v[208:211], v147 offset:16384
	ds_read_b128 v[212:215], v147 offset:17408
	ds_read_b128 v[226:229], v147 offset:18432
	ds_read_b128 v[230:233], v147 offset:19456
	ds_read_b128 v[234:237], v147 offset:20480
	ds_read_b128 v[238:241], v147 offset:21504
	ds_read_b128 v[242:245], v147 offset:22528
	ds_read_b128 v[246:249], v147 offset:23552
	global_load_lds_dwordx4 v[142:143], off
	s_add_i32 m0, s39, 0x2000
	s_add_u32 s72, s26, 0x80000
	v_lshl_add_u64 v[148:149], s[26:27], 0, v[160:161]
	s_addc_u32 s73, s27, 0
	s_add_i32 s39, s65, s36
	global_load_lds_dwordx4 v[148:149], off
	v_lshl_add_u64 v[198:199], s[72:73], 0, v[156:157]
	s_mov_b32 m0, s39
	v_lshl_add_u64 v[216:217], s[28:29], 0, v[158:159]
	global_load_lds_dwordx4 v[198:199], off
	v_lshl_add_u64 v[198:199], s[72:73], 0, v[160:161]
	s_add_i32 m0, s39, 0x2000
	s_nop 0
	global_load_lds_dwordx4 v[198:199], off
	v_lshl_add_u64 v[198:199], s[28:29], 0, v[154:155]
	s_mov_b32 m0, s23
	s_nop 0
	global_load_lds_dwordx4 v[198:199], off
	s_mov_b32 m0, s37
	s_nop 0
	global_load_lds_dwordx4 v[216:217], off
	s_waitcnt vmcnt(8)
	s_waitcnt lgkmcnt(0)
	s_barrier
; #define PG8_STAGE(bufoff, gbase, voff) do { _Pragma("unroll") for (int _i = 0; _i < 2; ++_i) \
;         __builtin_amdgcn_global_load_lds((const unsigned*)((const char*)(gbase) + (voff)[_i]), (LAS unsigned*)(lds + (bufoff) + ldsw + _i * 8192), 16, 0, 0); } while (0)
; #define PG8_LDA(dst, b, h) do { _Pragma("unroll") for (int m = 0; m < 4; ++m) _Pragma("unroll") for (int k = 0; k < 2; ++k) dst[m][k] = *(const LAS bf16x8*)(lds + PG8_SA(b, h) + aoff + m * 2048 + k * 1024); } while (0)
; #define PG8_LDB(dst, b, h) do { _Pragma("unroll") for (int n = 0; n < 2; ++n) _Pragma("unroll") for (int k = 0; k < 2; ++k) dst[n][k] = *(const LAS bf16x8*)(lds + PG8_SB(b, h) + boff + n * 2048 + k * 1024); } while (0)
; #define PG8_MMA(ai, bj, At, Bt) do { __builtin_amdgcn_s_setprio(1); _Pragma("unroll") for (int m = 0; m < 4; ++m) _Pragma("unroll") for (int n = 0; n < 2; ++n) _Pragma("unroll") for (int k = 0; k < 2; ++k) \
;         acc[ai][bj][m][n] = __builtin_amdgcn_mfma_f32_16x16x32_bf16(Bt[n][k], At[m][k], acc[ai][bj][m][n], 0, 0, 0); __builtin_amdgcn_s_setprio(0); } while (0)
; #define PG8_WAIT_V(n) asm volatile("s_waitcnt vmcnt(" #n ")" ::: "memory")
; #define PG8_WAIT_L(n) asm volatile("s_waitcnt lgkmcnt(" #n ")" ::: "memory")
; #define PG8_BAR __builtin_amdgcn_s_barrier()
; #define PG8_SCHED __builtin_amdgcn_sched_barrier(0)
; template <class Epi, class Sched>
; __device__ __forceinline__ void gemm_phase(LAS unsigned char* lds, const Gemm g, const Sched& S, const Epi& E) {
;     ...
;             PG8_WAIT_V(8); PG8_WAIT_L(0); PG8_BAR; PG8_MMA(1, 0, At, B0); PG8_MMA(1, 1, At, B1); PG8_BAR; PG8_SCHED;
;             PG8_LDB(B0, 1, 0); PG8_LDB(B1, 1, 1); PG8_SCHED; PG8_LDA(At, 1, 0); PG8_STAGE(PG8_SA(0, 1), a2 + hstep, voffA);
;             PG8_WAIT_V(8); PG8_WAIT_L(0); PG8_BAR; PG8_MMA(0, 0, At, B0); PG8_MMA(0, 1, At, B1); PG8_BAR; PG8_SCHED;
	s_setprio 1
	s_waitcnt lgkmcnt(0)
	v_mfma_f32_16x16x32_bf16 v[92:95], v[170:173], v[208:211], v[92:95]
	v_mfma_f32_16x16x32_bf16 v[88:91], v[178:181], v[208:211], v[88:91]
	v_mfma_f32_16x16x32_bf16 v[84:87], v[170:173], v[226:229], v[84:87]
	v_mfma_f32_16x16x32_bf16 v[80:83], v[178:181], v[226:229], v[80:83]
	v_mfma_f32_16x16x32_bf16 v[76:79], v[170:173], v[234:237], v[76:79]
	v_mfma_f32_16x16x32_bf16 v[72:75], v[178:181], v[234:237], v[72:75]
	v_mfma_f32_16x16x32_bf16 v[68:71], v[170:173], v[242:245], v[68:71]
	v_mfma_f32_16x16x32_bf16 v[64:67], v[178:181], v[242:245], v[64:67]
	v_mfma_f32_16x16x32_bf16 v[92:95], v[174:177], v[212:215], v[92:95]
	v_mfma_f32_16x16x32_bf16 v[88:91], v[182:185], v[212:215], v[88:91]
	v_mfma_f32_16x16x32_bf16 v[84:87], v[174:177], v[230:233], v[84:87]
	v_mfma_f32_16x16x32_bf16 v[80:83], v[182:185], v[230:233], v[80:83]
	v_mfma_f32_16x16x32_bf16 v[76:79], v[174:177], v[238:241], v[76:79]
	v_mfma_f32_16x16x32_bf16 v[72:75], v[182:185], v[238:241], v[72:75]
	v_mfma_f32_16x16x32_bf16 v[68:71], v[174:177], v[246:249], v[68:71]
	v_mfma_f32_16x16x32_bf16 v[64:67], v[182:185], v[246:249], v[64:67]
	v_mfma_f32_16x16x32_bf16 v[28:31], v[186:189], v[208:211], v[28:31]
	v_mfma_f32_16x16x32_bf16 v[24:27], v[194:197], v[208:211], v[24:27]
	v_mfma_f32_16x16x32_bf16 v[20:23], v[186:189], v[226:229], v[20:23]
	v_mfma_f32_16x16x32_bf16 v[16:19], v[194:197], v[226:229], v[16:19]
	v_mfma_f32_16x16x32_bf16 v[12:15], v[186:189], v[234:237], v[12:15]
	v_mfma_f32_16x16x32_bf16 v[8:11], v[194:197], v[234:237], v[8:11]
	v_mfma_f32_16x16x32_bf16 v[4:7], v[186:189], v[242:245], v[4:7]
	v_mfma_f32_16x16x32_bf16 v[0:3], v[194:197], v[242:245], v[0:3]
	v_mfma_f32_16x16x32_bf16 v[28:31], v[190:193], v[212:215], v[28:31]
	v_mfma_f32_16x16x32_bf16 v[24:27], v[204:207], v[212:215], v[24:27]
	v_mfma_f32_16x16x32_bf16 v[20:23], v[190:193], v[230:233], v[20:23]
	v_mfma_f32_16x16x32_bf16 v[16:19], v[204:207], v[230:233], v[16:19]
	v_mfma_f32_16x16x32_bf16 v[12:15], v[190:193], v[238:241], v[12:15]
	v_mfma_f32_16x16x32_bf16 v[8:11], v[204:207], v[238:241], v[8:11]
	v_mfma_f32_16x16x32_bf16 v[4:7], v[190:193], v[246:249], v[4:7]
	v_mfma_f32_16x16x32_bf16 v[0:3], v[204:207], v[246:249], v[0:3]
	s_setprio 0
	s_barrier
	s_add_i32 s39, 0, 0x18000
	v_add_u32_e32 v165, s39, v141
	s_add_i32 s72, 0, 0x1c000
	ds_read_b128 v[170:173], v165
	ds_read_b128 v[174:177], v165 offset:1024
	ds_read_b128 v[178:181], v165 offset:2048
	ds_read_b128 v[182:185], v165 offset:3072
	v_add_u32_e32 v165, s72, v141
	ds_read_b128 v[186:189], v165
	ds_read_b128 v[190:193], v165 offset:1024
	ds_read_b128 v[194:197], v165 offset:2048
	ds_read_b128 v[204:207], v165 offset:3072
	s_add_u32 s28, s28, 0x80000
	s_addc_u32 s29, s29, 0
	s_mov_b32 m0, s46
	v_lshl_add_u64 v[250:251], s[28:29], 0, v[154:155]
	ds_read_b128 v[208:211], v147 offset:32768
	ds_read_b128 v[212:215], v147 offset:33792
	ds_read_b128 v[226:229], v147 offset:34816
	ds_read_b128 v[230:233], v147 offset:35840
	ds_read_b128 v[234:237], v147 offset:36864
	ds_read_b128 v[238:241], v147 offset:37888
	ds_read_b128 v[242:245], v147 offset:38912
	ds_read_b128 v[246:249], v147 offset:39936
	global_load_lds_dwordx4 v[250:251], off
	v_lshl_add_u64 v[250:251], s[28:29], 0, v[158:159]
	s_mov_b32 m0, s47
	s_nop 0
	global_load_lds_dwordx4 v[250:251], off
	s_waitcnt vmcnt(8)
	s_waitcnt lgkmcnt(0)
	s_barrier
	s_setprio 1
	s_waitcnt lgkmcnt(0)
	v_mfma_f32_16x16x32_bf16 v[124:127], v[170:173], v[208:211], v[124:127]
	v_mfma_f32_16x16x32_bf16 v[120:123], v[178:181], v[208:211], v[120:123]
	v_mfma_f32_16x16x32_bf16 v[116:119], v[170:173], v[226:229], v[116:119]
	v_mfma_f32_16x16x32_bf16 v[112:115], v[178:181], v[226:229], v[112:115]
	v_mfma_f32_16x16x32_bf16 v[108:111], v[170:173], v[234:237], v[108:111]
	v_mfma_f32_16x16x32_bf16 v[104:107], v[178:181], v[234:237], v[104:107]
	v_mfma_f32_16x16x32_bf16 v[100:103], v[170:173], v[242:245], v[100:103]
	v_mfma_f32_16x16x32_bf16 v[96:99], v[178:181], v[242:245], v[96:99]
	v_mfma_f32_16x16x32_bf16 v[124:127], v[174:177], v[212:215], v[124:127]
	v_mfma_f32_16x16x32_bf16 v[120:123], v[182:185], v[212:215], v[120:123]
	v_mfma_f32_16x16x32_bf16 v[116:119], v[174:177], v[230:233], v[116:119]
	v_mfma_f32_16x16x32_bf16 v[112:115], v[182:185], v[230:233], v[112:115]
	v_mfma_f32_16x16x32_bf16 v[108:111], v[174:177], v[238:241], v[108:111]
	v_mfma_f32_16x16x32_bf16 v[104:107], v[182:185], v[238:241], v[104:107]
	v_mfma_f32_16x16x32_bf16 v[100:103], v[174:177], v[246:249], v[100:103]
	v_mfma_f32_16x16x32_bf16 v[96:99], v[182:185], v[246:249], v[96:99]
	v_mfma_f32_16x16x32_bf16 v[60:63], v[186:189], v[208:211], v[60:63]
	v_mfma_f32_16x16x32_bf16 v[56:59], v[194:197], v[208:211], v[56:59]
	v_mfma_f32_16x16x32_bf16 v[52:55], v[186:189], v[226:229], v[52:55]
	v_mfma_f32_16x16x32_bf16 v[48:51], v[194:197], v[226:229], v[48:51]
	v_mfma_f32_16x16x32_bf16 v[44:47], v[186:189], v[234:237], v[44:47]
	v_mfma_f32_16x16x32_bf16 v[40:43], v[194:197], v[234:237], v[40:43]
	v_mfma_f32_16x16x32_bf16 v[36:39], v[186:189], v[242:245], v[36:39]
	v_mfma_f32_16x16x32_bf16 v[32:35], v[194:197], v[242:245], v[32:35]
	v_mfma_f32_16x16x32_bf16 v[60:63], v[190:193], v[212:215], v[60:63]
	v_mfma_f32_16x16x32_bf16 v[56:59], v[204:207], v[212:215], v[56:59]
	v_mfma_f32_16x16x32_bf16 v[52:55], v[190:193], v[230:233], v[52:55]
	v_mfma_f32_16x16x32_bf16 v[48:51], v[204:207], v[230:233], v[48:51]
	v_mfma_f32_16x16x32_bf16 v[44:47], v[190:193], v[238:241], v[44:47]
	v_mfma_f32_16x16x32_bf16 v[40:43], v[204:207], v[238:241], v[40:43]
	v_mfma_f32_16x16x32_bf16 v[36:39], v[190:193], v[246:249], v[36:39]
	v_mfma_f32_16x16x32_bf16 v[32:35], v[204:207], v[246:249], v[32:35]
	s_setprio 0
	s_barrier
; #define PG8_STAGE(bufoff, gbase, voff) do { _Pragma("unroll") for (int _i = 0; _i < 2; ++_i) \
;         __builtin_amdgcn_global_load_lds((const unsigned*)((const char*)(gbase) + (voff)[_i]), (LAS unsigned*)(lds + (bufoff) + ldsw + _i * 8192), 16, 0, 0); } while (0)
; #define PG8_LDA(dst, b, h) do { _Pragma("unroll") for (int m = 0; m < 4; ++m) _Pragma("unroll") for (int k = 0; k < 2; ++k) dst[m][k] = *(const LAS bf16x8*)(lds + PG8_SA(b, h) + aoff + m * 2048 + k * 1024); } while (0)
; #define PG8_MMA(ai, bj, At, Bt) do { __builtin_amdgcn_s_setprio(1); _Pragma("unroll") for (int m = 0; m < 4; ++m) _Pragma("unroll") for (int n = 0; n < 2; ++n) _Pragma("unroll") for (int k = 0; k < 2; ++k) \
;         acc[ai][bj][m][n] = __builtin_amdgcn_mfma_f32_16x16x32_bf16(Bt[n][k], At[m][k], acc[ai][bj][m][n], 0, 0, 0); __builtin_amdgcn_s_setprio(0); } while (0)
; #define PG8_WAIT_V(n) asm volatile("s_waitcnt vmcnt(" #n ")" ::: "memory")
; #define PG8_WAIT_L(n) asm volatile("s_waitcnt lgkmcnt(" #n ")" ::: "memory")
; #define PG8_BAR __builtin_amdgcn_s_barrier()
; #define PG8_SCHED __builtin_amdgcn_sched_barrier(0)
; template <class Epi, class Sched>
; __device__ __forceinline__ void gemm_phase(LAS unsigned char* lds, const Gemm g, const Sched& S, const Epi& E) {
;     ...
;             PG8_LDA(At, 1, 1); PG8_STAGE(PG8_SB(1, 0), b3, voffB); PG8_STAGE(PG8_SB(1, 1), b3 + hstep, voffB); PG8_STAGE(PG8_SA(1, 0), a3, voffA);
;             PG8_WAIT_V(8); PG8_WAIT_L(0); PG8_BAR; PG8_MMA(1, 0, At, B0); PG8_MMA(1, 1, At, B1); PG8_BAR; PG8_SCHED;
;         }
	s_add_i32 s28, s39, s36
	v_lshl_add_u64 v[142:143], v[142:143], 0, s[8:9]
	s_mov_b32 m0, s28
	ds_read_b128 v[208:211], v147 offset:49152
	ds_read_b128 v[212:215], v147 offset:50176
	ds_read_b128 v[226:229], v147 offset:51200
	ds_read_b128 v[230:233], v147 offset:52224
	ds_read_b128 v[234:237], v147 offset:53248
	ds_read_b128 v[238:241], v147 offset:54272
	ds_read_b128 v[242:245], v147 offset:55296
	ds_read_b128 v[246:249], v147 offset:56320
	global_load_lds_dwordx4 v[142:143], off
	s_add_i32 m0, s28, 0x2000
	s_add_u32 s26, s26, 0x80080
	v_lshl_add_u64 v[142:143], v[148:149], 0, s[8:9]
	s_addc_u32 s27, s27, 0
	s_add_i32 s28, s72, s36
	global_load_lds_dwordx4 v[142:143], off
	v_lshl_add_u64 v[142:143], s[26:27], 0, v[156:157]
	s_mov_b32 m0, s28
	s_nop 0
	global_load_lds_dwordx4 v[142:143], off
	v_lshl_add_u64 v[142:143], s[26:27], 0, v[160:161]
	s_add_i32 m0, s28, 0x2000
	s_nop 0
	global_load_lds_dwordx4 v[142:143], off
	v_lshl_add_u64 v[142:143], v[198:199], 0, s[8:9]
	s_mov_b32 m0, s53
	s_nop 0
	global_load_lds_dwordx4 v[142:143], off
	v_lshl_add_u64 v[142:143], v[216:217], 0, s[8:9]
	s_mov_b32 m0, s54
	s_nop 0
	global_load_lds_dwordx4 v[142:143], off
	s_waitcnt vmcnt(8)
	s_waitcnt lgkmcnt(0)
	s_barrier
	s_setprio 1
	s_waitcnt lgkmcnt(0)
	v_mfma_f32_16x16x32_bf16 v[92:95], v[170:173], v[208:211], v[92:95]
	v_mfma_f32_16x16x32_bf16 v[88:91], v[178:181], v[208:211], v[88:91]
	v_mfma_f32_16x16x32_bf16 v[84:87], v[170:173], v[226:229], v[84:87]
	v_mfma_f32_16x16x32_bf16 v[80:83], v[178:181], v[226:229], v[80:83]
	v_mfma_f32_16x16x32_bf16 v[76:79], v[170:173], v[234:237], v[76:79]
	v_mfma_f32_16x16x32_bf16 v[72:75], v[178:181], v[234:237], v[72:75]
	v_mfma_f32_16x16x32_bf16 v[68:71], v[170:173], v[242:245], v[68:71]
	v_mfma_f32_16x16x32_bf16 v[64:67], v[178:181], v[242:245], v[64:67]
	v_mfma_f32_16x16x32_bf16 v[92:95], v[174:177], v[212:215], v[92:95]
	v_mfma_f32_16x16x32_bf16 v[88:91], v[182:185], v[212:215], v[88:91]
	v_mfma_f32_16x16x32_bf16 v[84:87], v[174:177], v[230:233], v[84:87]
	v_mfma_f32_16x16x32_bf16 v[80:83], v[182:185], v[230:233], v[80:83]
	v_mfma_f32_16x16x32_bf16 v[76:79], v[174:177], v[238:241], v[76:79]
	v_mfma_f32_16x16x32_bf16 v[72:75], v[182:185], v[238:241], v[72:75]
	v_mfma_f32_16x16x32_bf16 v[68:71], v[174:177], v[246:249], v[68:71]
	v_mfma_f32_16x16x32_bf16 v[64:67], v[182:185], v[246:249], v[64:67]
	v_mfma_f32_16x16x32_bf16 v[28:31], v[186:189], v[208:211], v[28:31]
	v_mfma_f32_16x16x32_bf16 v[24:27], v[194:197], v[208:211], v[24:27]
	v_mfma_f32_16x16x32_bf16 v[20:23], v[186:189], v[226:229], v[20:23]
	v_mfma_f32_16x16x32_bf16 v[16:19], v[194:197], v[226:229], v[16:19]
	v_mfma_f32_16x16x32_bf16 v[12:15], v[186:189], v[234:237], v[12:15]
	v_mfma_f32_16x16x32_bf16 v[8:11], v[194:197], v[234:237], v[8:11]
	v_mfma_f32_16x16x32_bf16 v[4:7], v[186:189], v[242:245], v[4:7]
	v_mfma_f32_16x16x32_bf16 v[0:3], v[194:197], v[242:245], v[0:3]
	v_mfma_f32_16x16x32_bf16 v[28:31], v[190:193], v[212:215], v[28:31]
	v_mfma_f32_16x16x32_bf16 v[24:27], v[204:207], v[212:215], v[24:27]
	v_mfma_f32_16x16x32_bf16 v[20:23], v[190:193], v[230:233], v[20:23]
	v_mfma_f32_16x16x32_bf16 v[16:19], v[204:207], v[230:233], v[16:19]
	v_mfma_f32_16x16x32_bf16 v[12:15], v[190:193], v[238:241], v[12:15]
	v_mfma_f32_16x16x32_bf16 v[8:11], v[204:207], v[238:241], v[8:11]
	v_mfma_f32_16x16x32_bf16 v[4:7], v[190:193], v[246:249], v[4:7]
	v_mfma_f32_16x16x32_bf16 v[0:3], v[204:207], v[246:249], v[0:3]
	s_setprio 0
	s_barrier
	s_add_i32 s38, s38, 2
	s_add_u32 s24, s24, 0x100
	s_addc_u32 s25, s25, 0
	s_add_u32 s17, s17, 0x100
	s_addc_u32 s33, s33, 0
	s_cmp_gt_u32 s38, 29
	s_cbranch_scc0 .LBB0_343
	s_and_b64 vcc, exec, s[10:11]
	v_readlane_b32 s97, v252, 39
	s_cbranch_vccz .LBB0_346
	s_barrier

; #define PG8_STAGE(bufoff, gbase, voff) do { _Pragma("unroll") for (int _i = 0; _i < 2; ++_i) \
;         __builtin_amdgcn_global_load_lds((const unsigned*)((const char*)(gbase) + (voff)[_i]), (LAS unsigned*)(lds + (bufoff) + ldsw + _i * 8192), 16, 0, 0); } while (0)
; #define PG8_LDA(dst, b, h) do { _Pragma("unroll") for (int m = 0; m < 4; ++m) _Pragma("unroll") for (int k = 0; k < 2; ++k) dst[m][k] = *(const LAS bf16x8*)(lds + PG8_SA(b, h) + aoff + m * 2048 + k * 1024); } while (0)
; #define PG8_LDB(dst, b, h) do { _Pragma("unroll") for (int n = 0; n < 2; ++n) _Pragma("unroll") for (int k = 0; k < 2; ++k) dst[n][k] = *(const LAS bf16x8*)(lds + PG8_SB(b, h) + boff + n * 2048 + k * 1024); } while (0)
; #define PG8_MMA(ai, bj, At, Bt) do { __builtin_amdgcn_s_setprio(1); _Pragma("unroll") for (int m = 0; m < 4; ++m) _Pragma("unroll") for (int n = 0; n < 2; ++n) _Pragma("unroll") for (int k = 0; k < 2; ++k) \
;         acc[ai][bj][m][n] = __builtin_amdgcn_mfma_f32_16x16x32_bf16(Bt[n][k], At[m][k], acc[ai][bj][m][n], 0, 0, 0); __builtin_amdgcn_s_setprio(0); } while (0)
; #define PG8_WAIT_V(n) asm volatile("s_waitcnt vmcnt(" #n ")" ::: "memory")
; #define PG8_WAIT_L(n) asm volatile("s_waitcnt lgkmcnt(" #n ")" ::: "memory")
; #define PG8_BAR __builtin_amdgcn_s_barrier()
; #define PG8_SCHED __builtin_amdgcn_sched_barrier(0)
; template <class Epi, class Sched>
; __device__ __forceinline__ void gemm_phase(LAS unsigned char* lds, const Gemm g, const Sched& S, const Epi& E) {
;     ...
;         for (int t = 0; t < nt; t += 2) {
;             const bool last = (t == nt - 2);
;             const char* a1 = cA + (size_t)(t + 1) * kstep;
;             const char* a2 = last ? nA : cA + (size_t)(t + 2) * kstep; const char* b2 = last ? nB : cB + (size_t)(t + 2) * kstep;
;             const char* a3 = a2 + kstep; const char* b3 = b2 + kstep;
;             PG8_LDB(B0, 0, 0); PG8_LDB(B1, 0, 1); PG8_SCHED; PG8_LDA(At, 0, 0); PG8_STAGE(PG8_SA(1, 1), a1 + hstep, voffA);
;             PG8_WAIT_V(8); PG8_WAIT_L(0); PG8_BAR; PG8_MMA(0, 0, At, B0); PG8_MMA(0, 1, At, B1); PG8_BAR; PG8_SCHED;
;             PG8_LDA(At, 0, 1); PG8_STAGE(PG8_SB(0, 0), b2, voffB); PG8_STAGE(PG8_SB(0, 1), b2 + hstep, voffB); PG8_STAGE(PG8_SA(0, 0), a2, voffA);
.LBB0_609:
	ds_read_b128 v[128:131], v203
	ds_read_b128 v[132:135], v203 offset:1024
	ds_read_b128 v[166:169], v203 offset:2048
	ds_read_b128 v[170:173], v203 offset:3072
	ds_read_b128 v[174:177], v204
	ds_read_b128 v[178:181], v204 offset:1024
	ds_read_b128 v[182:185], v204 offset:2048
	ds_read_b128 v[186:189], v204 offset:3072
	s_add_u32 s34, s30, 0xfff80080
	s_addc_u32 s35, s31, -1
	s_cmp_eq_u32 s62, 28
	s_cselect_b32 s37, s2, s35
	s_cselect_b32 s36, s14, s34
	s_cselect_b32 s35, s15, s33
	s_cselect_b32 s34, s19, s21
	v_lshl_add_u64 v[150:151], s[30:31], 0, v[142:143]
	s_add_i32 m0, s27, 0xc000
	ds_read_b128 v[190:193], v205
	ds_read_b128 v[194:197], v205 offset:1024
	ds_read_b128 v[208:211], v205 offset:2048
	ds_read_b128 v[212:215], v205 offset:3072
	ds_read_b128 v[226:229], v205 offset:4096
	ds_read_b128 v[230:233], v205 offset:5120
	ds_read_b128 v[234:237], v205 offset:6144
	ds_read_b128 v[238:241], v205 offset:7168
	global_load_lds_dwordx4 v[150:151], off
	v_lshl_add_u64 v[150:151], s[30:31], 0, v[144:145]
	s_add_i32 m0, s27, 0xe000
	s_nop 0
	global_load_lds_dwordx4 v[150:151], off
	s_waitcnt vmcnt(8)
	s_waitcnt lgkmcnt(0)
	s_barrier
	s_setprio 1
	s_waitcnt lgkmcnt(0)
	v_mfma_f32_16x16x32_bf16 v[124:127], v[128:131], v[190:193], v[124:127]
	v_mfma_f32_16x16x32_bf16 v[120:123], v[166:169], v[190:193], v[120:123]
	v_mfma_f32_16x16x32_bf16 v[116:119], v[128:131], v[208:211], v[116:119]
	v_mfma_f32_16x16x32_bf16 v[112:115], v[166:169], v[208:211], v[112:115]
	v_mfma_f32_16x16x32_bf16 v[108:111], v[128:131], v[226:229], v[108:111]
	v_mfma_f32_16x16x32_bf16 v[104:107], v[166:169], v[226:229], v[104:107]
	v_mfma_f32_16x16x32_bf16 v[100:103], v[128:131], v[234:237], v[100:103]
	v_mfma_f32_16x16x32_bf16 v[96:99], v[166:169], v[234:237], v[96:99]
	v_mfma_f32_16x16x32_bf16 v[124:127], v[132:135], v[194:197], v[124:127]
	v_mfma_f32_16x16x32_bf16 v[120:123], v[170:173], v[194:197], v[120:123]
	v_mfma_f32_16x16x32_bf16 v[116:119], v[132:135], v[212:215], v[116:119]
	v_mfma_f32_16x16x32_bf16 v[112:115], v[170:173], v[212:215], v[112:115]
	v_mfma_f32_16x16x32_bf16 v[108:111], v[132:135], v[230:233], v[108:111]
	v_mfma_f32_16x16x32_bf16 v[104:107], v[170:173], v[230:233], v[104:107]
	v_mfma_f32_16x16x32_bf16 v[100:103], v[132:135], v[238:241], v[100:103]
	v_mfma_f32_16x16x32_bf16 v[96:99], v[170:173], v[238:241], v[96:99]
	v_mfma_f32_16x16x32_bf16 v[60:63], v[174:177], v[190:193], v[60:63]
	v_mfma_f32_16x16x32_bf16 v[56:59], v[182:185], v[190:193], v[56:59]
	v_mfma_f32_16x16x32_bf16 v[52:55], v[174:177], v[208:211], v[52:55]
	v_mfma_f32_16x16x32_bf16 v[48:51], v[182:185], v[208:211], v[48:51]
	v_mfma_f32_16x16x32_bf16 v[44:47], v[174:177], v[226:229], v[44:47]
	v_mfma_f32_16x16x32_bf16 v[40:43], v[182:185], v[226:229], v[40:43]
	v_mfma_f32_16x16x32_bf16 v[36:39], v[174:177], v[234:237], v[36:39]
	v_mfma_f32_16x16x32_bf16 v[32:35], v[182:185], v[234:237], v[32:35]
	v_mfma_f32_16x16x32_bf16 v[60:63], v[178:181], v[194:197], v[60:63]
	v_mfma_f32_16x16x32_bf16 v[56:59], v[186:189], v[194:197], v[56:59]
	v_mfma_f32_16x16x32_bf16 v[52:55], v[178:181], v[212:215], v[52:55]
	v_mfma_f32_16x16x32_bf16 v[48:51], v[186:189], v[212:215], v[48:51]
	v_mfma_f32_16x16x32_bf16 v[44:47], v[178:181], v[230:233], v[44:47]
	v_mfma_f32_16x16x32_bf16 v[40:43], v[186:189], v[230:233], v[40:43]
	v_mfma_f32_16x16x32_bf16 v[36:39], v[178:181], v[238:241], v[36:39]
	v_mfma_f32_16x16x32_bf16 v[32:35], v[186:189], v[238:241], v[32:35]
	s_setprio 0
	s_barrier
	s_add_i32 s63, s54, s46
	v_lshl_add_u64 v[150:151], s[34:35], 0, v[156:157]
	s_mov_b32 m0, s63
	ds_read_b128 v[190:193], v205 offset:16384
	ds_read_b128 v[194:197], v205 offset:17408
	ds_read_b128 v[208:211], v205 offset:18432
	ds_read_b128 v[212:215], v205 offset:19456
	ds_read_b128 v[226:229], v205 offset:20480
	ds_read_b128 v[230:233], v205 offset:21504
	ds_read_b128 v[234:237], v205 offset:22528
	ds_read_b128 v[238:241], v205 offset:23552
	global_load_lds_dwordx4 v[150:151], off
	s_add_i32 m0, s63, 0x2000
	s_add_u32 s64, s34, 0x80000
	v_lshl_add_u64 v[198:199], s[34:35], 0, v[160:161]
	s_addc_u32 s65, s35, 0
	s_add_i32 s63, s55, s46
	global_load_lds_dwordx4 v[198:199], off
	v_lshl_add_u64 v[216:217], s[64:65], 0, v[156:157]
	s_mov_b32 m0, s63
	v_lshl_add_u64 v[242:243], s[36:37], 0, v[158:159]
	global_load_lds_dwordx4 v[216:217], off
	v_lshl_add_u64 v[216:217], s[64:65], 0, v[160:161]
	s_add_i32 m0, s63, 0x2000
	s_nop 0
	global_load_lds_dwordx4 v[216:217], off
	v_lshl_add_u64 v[216:217], s[36:37], 0, v[154:155]
	s_mov_b32 m0, s27
	s_nop 0
	global_load_lds_dwordx4 v[216:217], off
	s_mov_b32 m0, s3
	s_nop 0
	global_load_lds_dwordx4 v[242:243], off
	s_waitcnt vmcnt(8)
	s_waitcnt lgkmcnt(0)
	s_barrier
; #define PG8_STAGE(bufoff, gbase, voff) do { _Pragma("unroll") for (int _i = 0; _i < 2; ++_i) \
;         __builtin_amdgcn_global_load_lds((const unsigned*)((const char*)(gbase) + (voff)[_i]), (LAS unsigned*)(lds + (bufoff) + ldsw + _i * 8192), 16, 0, 0); } while (0)
; #define PG8_LDA(dst, b, h) do { _Pragma("unroll") for (int m = 0; m < 4; ++m) _Pragma("unroll") for (int k = 0; k < 2; ++k) dst[m][k] = *(const LAS bf16x8*)(lds + PG8_SA(b, h) + aoff + m * 2048 + k * 1024); } while (0)
; #define PG8_LDB(dst, b, h) do { _Pragma("unroll") for (int n = 0; n < 2; ++n) _Pragma("unroll") for (int k = 0; k < 2; ++k) dst[n][k] = *(const LAS bf16x8*)(lds + PG8_SB(b, h) + boff + n * 2048 + k * 1024); } while (0)
; #define PG8_MMA(ai, bj, At, Bt) do { __builtin_amdgcn_s_setprio(1); _Pragma("unroll") for (int m = 0; m < 4; ++m) _Pragma("unroll") for (int n = 0; n < 2; ++n) _Pragma("unroll") for (int k = 0; k < 2; ++k) \
;         acc[ai][bj][m][n] = __builtin_amdgcn_mfma_f32_16x16x32_bf16(Bt[n][k], At[m][k], acc[ai][bj][m][n], 0, 0, 0); __builtin_amdgcn_s_setprio(0); } while (0)
; #define PG8_WAIT_V(n) asm volatile("s_waitcnt vmcnt(" #n ")" ::: "memory")
; #define PG8_WAIT_L(n) asm volatile("s_waitcnt lgkmcnt(" #n ")" ::: "memory")
; #define PG8_BAR __builtin_amdgcn_s_barrier()
; #define PG8_SCHED __builtin_amdgcn_sched_barrier(0)
; template <class Epi, class Sched>
; __device__ __forceinline__ void gemm_phase(LAS unsigned char* lds, const Gemm g, const Sched& S, const Epi& E) {
;     ...
;             PG8_WAIT_V(8); PG8_WAIT_L(0); PG8_BAR; PG8_MMA(1, 0, At, B0); PG8_MMA(1, 1, At, B1); PG8_BAR; PG8_SCHED;
;             PG8_LDB(B0, 1, 0); PG8_LDB(B1, 1, 1); PG8_SCHED; PG8_LDA(At, 1, 0); PG8_STAGE(PG8_SA(0, 1), a2 + hstep, voffA);
;             PG8_WAIT_V(8); PG8_WAIT_L(0); PG8_BAR; PG8_MMA(0, 0, At, B0); PG8_MMA(0, 1, At, B1); PG8_BAR; PG8_SCHED;
	s_setprio 1
	s_waitcnt lgkmcnt(0)
	v_mfma_f32_16x16x32_bf16 v[92:95], v[128:131], v[190:193], v[92:95]
	v_mfma_f32_16x16x32_bf16 v[88:91], v[166:169], v[190:193], v[88:91]
	v_mfma_f32_16x16x32_bf16 v[84:87], v[128:131], v[208:211], v[84:87]
	v_mfma_f32_16x16x32_bf16 v[80:83], v[166:169], v[208:211], v[80:83]
	v_mfma_f32_16x16x32_bf16 v[76:79], v[128:131], v[226:229], v[76:79]
	v_mfma_f32_16x16x32_bf16 v[72:75], v[166:169], v[226:229], v[72:75]
	v_mfma_f32_16x16x32_bf16 v[68:71], v[128:131], v[234:237], v[68:71]
	v_mfma_f32_16x16x32_bf16 v[64:67], v[166:169], v[234:237], v[64:67]
	v_mfma_f32_16x16x32_bf16 v[92:95], v[132:135], v[194:197], v[92:95]
	v_mfma_f32_16x16x32_bf16 v[88:91], v[170:173], v[194:197], v[88:91]
	v_mfma_f32_16x16x32_bf16 v[84:87], v[132:135], v[212:215], v[84:87]
	v_mfma_f32_16x16x32_bf16 v[80:83], v[170:173], v[212:215], v[80:83]
	v_mfma_f32_16x16x32_bf16 v[76:79], v[132:135], v[230:233], v[76:79]
	v_mfma_f32_16x16x32_bf16 v[72:75], v[170:173], v[230:233], v[72:75]
	v_mfma_f32_16x16x32_bf16 v[68:71], v[132:135], v[238:241], v[68:71]
	v_mfma_f32_16x16x32_bf16 v[64:67], v[170:173], v[238:241], v[64:67]
	v_mfma_f32_16x16x32_bf16 v[28:31], v[174:177], v[190:193], v[28:31]
	v_mfma_f32_16x16x32_bf16 v[24:27], v[182:185], v[190:193], v[24:27]
	v_mfma_f32_16x16x32_bf16 v[20:23], v[174:177], v[208:211], v[20:23]
	v_mfma_f32_16x16x32_bf16 v[16:19], v[182:185], v[208:211], v[16:19]
	v_mfma_f32_16x16x32_bf16 v[12:15], v[174:177], v[226:229], v[12:15]
	v_mfma_f32_16x16x32_bf16 v[8:11], v[182:185], v[226:229], v[8:11]
	v_mfma_f32_16x16x32_bf16 v[4:7], v[174:177], v[234:237], v[4:7]
	v_mfma_f32_16x16x32_bf16 v[0:3], v[182:185], v[234:237], v[0:3]
	v_mfma_f32_16x16x32_bf16 v[28:31], v[178:181], v[194:197], v[28:31]
	v_mfma_f32_16x16x32_bf16 v[24:27], v[186:189], v[194:197], v[24:27]
	v_mfma_f32_16x16x32_bf16 v[20:23], v[178:181], v[212:215], v[20:23]
	v_mfma_f32_16x16x32_bf16 v[16:19], v[186:189], v[212:215], v[16:19]
	v_mfma_f32_16x16x32_bf16 v[12:15], v[178:181], v[230:233], v[12:15]
	v_mfma_f32_16x16x32_bf16 v[8:11], v[186:189], v[230:233], v[8:11]
	v_mfma_f32_16x16x32_bf16 v[4:7], v[178:181], v[238:241], v[4:7]
	v_mfma_f32_16x16x32_bf16 v[0:3], v[186:189], v[238:241], v[0:3]
	s_setprio 0
	s_barrier
	s_add_i32 s63, 0, 0x18000
	s_add_i32 s64, 0, 0x1c000
	v_add_u32_e32 v170, s63, v141
	v_add_u32_e32 v186, s64, v141
	ds_read_b128 v[128:131], v170
	ds_read_b128 v[132:135], v170 offset:1024
	ds_read_b128 v[166:169], v170 offset:2048
	ds_read_b128 v[170:173], v170 offset:3072
	ds_read_b128 v[174:177], v186
	ds_read_b128 v[178:181], v186 offset:1024
	ds_read_b128 v[182:185], v186 offset:2048
	ds_read_b128 v[186:189], v186 offset:3072
	s_add_u32 s36, s36, 0x80000
	s_addc_u32 s37, s37, 0
	s_mov_b32 m0, s29
	v_lshl_add_u64 v[244:245], s[36:37], 0, v[154:155]
	ds_read_b128 v[190:193], v205 offset:32768
	ds_read_b128 v[194:197], v205 offset:33792
	ds_read_b128 v[208:211], v205 offset:34816
	ds_read_b128 v[212:215], v205 offset:35840
	ds_read_b128 v[226:229], v205 offset:36864
	ds_read_b128 v[230:233], v205 offset:37888
	ds_read_b128 v[234:237], v205 offset:38912
	ds_read_b128 v[238:241], v205 offset:39936
	global_load_lds_dwordx4 v[244:245], off
	v_lshl_add_u64 v[244:245], s[36:37], 0, v[158:159]
	s_mov_b32 m0, s47
	s_nop 0
	global_load_lds_dwordx4 v[244:245], off
	s_waitcnt vmcnt(8)
	s_waitcnt lgkmcnt(0)
	s_barrier
	s_setprio 1
	s_waitcnt lgkmcnt(0)
	v_mfma_f32_16x16x32_bf16 v[124:127], v[128:131], v[190:193], v[124:127]
	v_mfma_f32_16x16x32_bf16 v[120:123], v[166:169], v[190:193], v[120:123]
	v_mfma_f32_16x16x32_bf16 v[116:119], v[128:131], v[208:211], v[116:119]
	v_mfma_f32_16x16x32_bf16 v[112:115], v[166:169], v[208:211], v[112:115]
	v_mfma_f32_16x16x32_bf16 v[108:111], v[128:131], v[226:229], v[108:111]
	v_mfma_f32_16x16x32_bf16 v[104:107], v[166:169], v[226:229], v[104:107]
	v_mfma_f32_16x16x32_bf16 v[100:103], v[128:131], v[234:237], v[100:103]
	v_mfma_f32_16x16x32_bf16 v[96:99], v[166:169], v[234:237], v[96:99]
	v_mfma_f32_16x16x32_bf16 v[124:127], v[132:135], v[194:197], v[124:127]
	v_mfma_f32_16x16x32_bf16 v[120:123], v[170:173], v[194:197], v[120:123]
	v_mfma_f32_16x16x32_bf16 v[116:119], v[132:135], v[212:215], v[116:119]
	v_mfma_f32_16x16x32_bf16 v[112:115], v[170:173], v[212:215], v[112:115]
	v_mfma_f32_16x16x32_bf16 v[108:111], v[132:135], v[230:233], v[108:111]
	v_mfma_f32_16x16x32_bf16 v[104:107], v[170:173], v[230:233], v[104:107]
	v_mfma_f32_16x16x32_bf16 v[100:103], v[132:135], v[238:241], v[100:103]
	v_mfma_f32_16x16x32_bf16 v[96:99], v[170:173], v[238:241], v[96:99]
	v_mfma_f32_16x16x32_bf16 v[60:63], v[174:177], v[190:193], v[60:63]
	v_mfma_f32_16x16x32_bf16 v[56:59], v[182:185], v[190:193], v[56:59]
	v_mfma_f32_16x16x32_bf16 v[52:55], v[174:177], v[208:211], v[52:55]
	v_mfma_f32_16x16x32_bf16 v[48:51], v[182:185], v[208:211], v[48:51]
	v_mfma_f32_16x16x32_bf16 v[44:47], v[174:177], v[226:229], v[44:47]
	v_mfma_f32_16x16x32_bf16 v[40:43], v[182:185], v[226:229], v[40:43]
	v_mfma_f32_16x16x32_bf16 v[36:39], v[174:177], v[234:237], v[36:39]
	v_mfma_f32_16x16x32_bf16 v[32:35], v[182:185], v[234:237], v[32:35]
	v_mfma_f32_16x16x32_bf16 v[60:63], v[178:181], v[194:197], v[60:63]
	v_mfma_f32_16x16x32_bf16 v[56:59], v[186:189], v[194:197], v[56:59]
	v_mfma_f32_16x16x32_bf16 v[52:55], v[178:181], v[212:215], v[52:55]
	v_mfma_f32_16x16x32_bf16 v[48:51], v[186:189], v[212:215], v[48:51]
	v_mfma_f32_16x16x32_bf16 v[44:47], v[178:181], v[230:233], v[44:47]
	v_mfma_f32_16x16x32_bf16 v[40:43], v[186:189], v[230:233], v[40:43]
	v_mfma_f32_16x16x32_bf16 v[36:39], v[178:181], v[238:241], v[36:39]
	v_mfma_f32_16x16x32_bf16 v[32:35], v[186:189], v[238:241], v[32:35]
	s_setprio 0
	s_barrier
; #define PG8_STAGE(bufoff, gbase, voff) do { _Pragma("unroll") for (int _i = 0; _i < 2; ++_i) \
;         __builtin_amdgcn_global_load_lds((const unsigned*)((const char*)(gbase) + (voff)[_i]), (LAS unsigned*)(lds + (bufoff) + ldsw + _i * 8192), 16, 0, 0); } while (0)
; #define PG8_LDA(dst, b, h) do { _Pragma("unroll") for (int m = 0; m < 4; ++m) _Pragma("unroll") for (int k = 0; k < 2; ++k) dst[m][k] = *(const LAS bf16x8*)(lds + PG8_SA(b, h) + aoff + m * 2048 + k * 1024); } while (0)
; #define PG8_MMA(ai, bj, At, Bt) do { __builtin_amdgcn_s_setprio(1); _Pragma("unroll") for (int m = 0; m < 4; ++m) _Pragma("unroll") for (int n = 0; n < 2; ++n) _Pragma("unroll") for (int k = 0; k < 2; ++k) \
;         acc[ai][bj][m][n] = __builtin_amdgcn_mfma_f32_16x16x32_bf16(Bt[n][k], At[m][k], acc[ai][bj][m][n], 0, 0, 0); __builtin_amdgcn_s_setprio(0); } while (0)
; #define PG8_WAIT_V(n) asm volatile("s_waitcnt vmcnt(" #n ")" ::: "memory")
; #define PG8_WAIT_L(n) asm volatile("s_waitcnt lgkmcnt(" #n ")" ::: "memory")
; #define PG8_BAR __builtin_amdgcn_s_barrier()
; #define PG8_SCHED __builtin_amdgcn_sched_barrier(0)
; template <class Epi, class Sched>
; __device__ __forceinline__ void gemm_phase(LAS unsigned char* lds, const Gemm g, const Sched& S, const Epi& E) {
;     ...
;             PG8_LDA(At, 1, 1); PG8_STAGE(PG8_SB(1, 0), b3, voffB); PG8_STAGE(PG8_SB(1, 1), b3 + hstep, voffB); PG8_STAGE(PG8_SA(1, 0), a3, voffA);
;             PG8_WAIT_V(8); PG8_WAIT_L(0); PG8_BAR; PG8_MMA(1, 0, At, B0); PG8_MMA(1, 1, At, B1); PG8_BAR; PG8_SCHED;
;         }
	s_add_i32 s36, s63, s46
	v_lshl_add_u64 v[150:151], v[150:151], 0, s[12:13]
	s_mov_b32 m0, s36
	ds_read_b128 v[190:193], v205 offset:49152
	ds_read_b128 v[194:197], v205 offset:50176
	ds_read_b128 v[208:211], v205 offset:51200
	ds_read_b128 v[212:215], v205 offset:52224
	ds_read_b128 v[226:229], v205 offset:53248
	ds_read_b128 v[230:233], v205 offset:54272
	ds_read_b128 v[234:237], v205 offset:55296
	ds_read_b128 v[238:241], v205 offset:56320
	global_load_lds_dwordx4 v[150:151], off
	s_add_i32 m0, s36, 0x2000
	s_add_u32 s34, s34, 0x80080
	v_lshl_add_u64 v[150:151], v[198:199], 0, s[12:13]
	s_addc_u32 s35, s35, 0
	s_add_i32 s36, s64, s46
	global_load_lds_dwordx4 v[150:151], off
	v_lshl_add_u64 v[150:151], s[34:35], 0, v[156:157]
	s_mov_b32 m0, s36
	s_nop 0
	global_load_lds_dwordx4 v[150:151], off
	v_lshl_add_u64 v[150:151], s[34:35], 0, v[160:161]
	s_add_i32 m0, s36, 0x2000
	s_nop 0
	global_load_lds_dwordx4 v[150:151], off
	v_lshl_add_u64 v[150:151], v[216:217], 0, s[12:13]
	s_mov_b32 m0, s42
	s_nop 0
	global_load_lds_dwordx4 v[150:151], off
	v_lshl_add_u64 v[150:151], v[242:243], 0, s[12:13]
	s_mov_b32 m0, s43
	s_nop 0
	global_load_lds_dwordx4 v[150:151], off
	s_waitcnt vmcnt(8)
	s_waitcnt lgkmcnt(0)
	s_barrier
	s_setprio 1
	s_waitcnt lgkmcnt(0)
	v_mfma_f32_16x16x32_bf16 v[92:95], v[128:131], v[190:193], v[92:95]
	v_mfma_f32_16x16x32_bf16 v[88:91], v[166:169], v[190:193], v[88:91]
	v_mfma_f32_16x16x32_bf16 v[84:87], v[128:131], v[208:211], v[84:87]
	v_mfma_f32_16x16x32_bf16 v[80:83], v[166:169], v[208:211], v[80:83]
	v_mfma_f32_16x16x32_bf16 v[76:79], v[128:131], v[226:229], v[76:79]
	v_mfma_f32_16x16x32_bf16 v[72:75], v[166:169], v[226:229], v[72:75]
	v_mfma_f32_16x16x32_bf16 v[68:71], v[128:131], v[234:237], v[68:71]
	v_mfma_f32_16x16x32_bf16 v[64:67], v[166:169], v[234:237], v[64:67]
	v_mfma_f32_16x16x32_bf16 v[92:95], v[132:135], v[194:197], v[92:95]
	v_mfma_f32_16x16x32_bf16 v[88:91], v[170:173], v[194:197], v[88:91]
	v_mfma_f32_16x16x32_bf16 v[84:87], v[132:135], v[212:215], v[84:87]
	v_mfma_f32_16x16x32_bf16 v[80:83], v[170:173], v[212:215], v[80:83]
	v_mfma_f32_16x16x32_bf16 v[76:79], v[132:135], v[230:233], v[76:79]
	v_mfma_f32_16x16x32_bf16 v[72:75], v[170:173], v[230:233], v[72:75]
	v_mfma_f32_16x16x32_bf16 v[68:71], v[132:135], v[238:241], v[68:71]
	v_mfma_f32_16x16x32_bf16 v[64:67], v[170:173], v[238:241], v[64:67]
	v_mfma_f32_16x16x32_bf16 v[28:31], v[174:177], v[190:193], v[28:31]
	v_mfma_f32_16x16x32_bf16 v[24:27], v[182:185], v[190:193], v[24:27]
	v_mfma_f32_16x16x32_bf16 v[20:23], v[174:177], v[208:211], v[20:23]
	v_mfma_f32_16x16x32_bf16 v[16:19], v[182:185], v[208:211], v[16:19]
	v_mfma_f32_16x16x32_bf16 v[12:15], v[174:177], v[226:229], v[12:15]
	v_mfma_f32_16x16x32_bf16 v[8:11], v[182:185], v[226:229], v[8:11]
	v_mfma_f32_16x16x32_bf16 v[4:7], v[174:177], v[234:237], v[4:7]
	v_mfma_f32_16x16x32_bf16 v[0:3], v[182:185], v[234:237], v[0:3]
	v_mfma_f32_16x16x32_bf16 v[28:31], v[178:181], v[194:197], v[28:31]
	v_mfma_f32_16x16x32_bf16 v[24:27], v[186:189], v[194:197], v[24:27]
	v_mfma_f32_16x16x32_bf16 v[20:23], v[178:181], v[212:215], v[20:23]
	v_mfma_f32_16x16x32_bf16 v[16:19], v[186:189], v[212:215], v[16:19]
	v_mfma_f32_16x16x32_bf16 v[12:15], v[178:181], v[230:233], v[12:15]
	v_mfma_f32_16x16x32_bf16 v[8:11], v[186:189], v[230:233], v[8:11]
	v_mfma_f32_16x16x32_bf16 v[4:7], v[178:181], v[238:241], v[4:7]
	v_mfma_f32_16x16x32_bf16 v[0:3], v[186:189], v[238:241], v[0:3]
	s_setprio 0
	s_barrier
	s_add_i32 s62, s62, 2
	s_add_u32 s30, s30, 0x100
	s_addc_u32 s31, s31, 0
	s_add_u32 s21, s21, 0x100
	s_addc_u32 s33, s33, 0
	s_cmp_gt_u32 s62, 29
	s_cbranch_scc0 .LBB0_609
	s_and_b64 vcc, exec, s[16:17]
	s_cbranch_vccz .LBB0_612
	s_barrier

; #define PG8_STAGE(bufoff, gbase, voff) do { _Pragma("unroll") for (int _i = 0; _i < 2; ++_i) \
;         __builtin_amdgcn_global_load_lds((const unsigned*)((const char*)(gbase) + (voff)[_i]), (LAS unsigned*)(lds + (bufoff) + ldsw + _i * 8192), 16, 0, 0); } while (0)
; #define PG8_LDA(dst, b, h) do { _Pragma("unroll") for (int m = 0; m < 4; ++m) _Pragma("unroll") for (int k = 0; k < 2; ++k) dst[m][k] = *(const LAS bf16x8*)(lds + PG8_SA(b, h) + aoff + m * 2048 + k * 1024); } while (0)
; #define PG8_LDB(dst, b, h) do { _Pragma("unroll") for (int n = 0; n < 2; ++n) _Pragma("unroll") for (int k = 0; k < 2; ++k) dst[n][k] = *(const LAS bf16x8*)(lds + PG8_SB(b, h) + boff + n * 2048 + k * 1024); } while (0)
; #define PG8_MMA(ai, bj, At, Bt) do { __builtin_amdgcn_s_setprio(1); _Pragma("unroll") for (int m = 0; m < 4; ++m) _Pragma("unroll") for (int n = 0; n < 2; ++n) _Pragma("unroll") for (int k = 0; k < 2; ++k) \
;         acc[ai][bj][m][n] = __builtin_amdgcn_mfma_f32_16x16x32_bf16(Bt[n][k], At[m][k], acc[ai][bj][m][n], 0, 0, 0); __builtin_amdgcn_s_setprio(0); } while (0)
; #define PG8_WAIT_V(n) asm volatile("s_waitcnt vmcnt(" #n ")" ::: "memory")
; #define PG8_WAIT_L(n) asm volatile("s_waitcnt lgkmcnt(" #n ")" ::: "memory")
; #define PG8_BAR __builtin_amdgcn_s_barrier()
; #define PG8_SCHED __builtin_amdgcn_sched_barrier(0)
; template <class Epi, class Sched>
; __device__ __forceinline__ void gemm_phase(LAS unsigned char* lds, const Gemm g, const Sched& S, const Epi& E) {
;     ...
;         for (int t = 0; t < nt; t += 2) {
;             const bool last = (t == nt - 2);
;             const char* a1 = cA + (size_t)(t + 1) * kstep;
;             const char* a2 = last ? nA : cA + (size_t)(t + 2) * kstep; const char* b2 = last ? nB : cB + (size_t)(t + 2) * kstep;
;             const char* a3 = a2 + kstep; const char* b3 = b2 + kstep;
;             PG8_LDB(B0, 0, 0); PG8_LDB(B1, 0, 1); PG8_SCHED; PG8_LDA(At, 0, 0); PG8_STAGE(PG8_SA(1, 1), a1 + hstep, voffA);
;             PG8_WAIT_V(8); PG8_WAIT_L(0); PG8_BAR; PG8_MMA(0, 0, At, B0); PG8_MMA(0, 1, At, B1); PG8_BAR; PG8_SCHED;
;             PG8_LDA(At, 0, 1); PG8_STAGE(PG8_SB(0, 0), b2, voffB); PG8_STAGE(PG8_SB(0, 1), b2 + hstep, voffB); PG8_STAGE(PG8_SA(0, 0), a2, voffA);
.LBB0_701:
	ds_read_b128 v[166:169], v147
	ds_read_b128 v[170:173], v147 offset:1024
	ds_read_b128 v[174:177], v147 offset:2048
	ds_read_b128 v[178:181], v147 offset:3072
	ds_read_b128 v[182:185], v149
	ds_read_b128 v[186:189], v149 offset:1024
	ds_read_b128 v[190:193], v149 offset:2048
	ds_read_b128 v[194:197], v149 offset:3072
	s_add_u32 s26, s24, 0xfff80080
	s_addc_u32 s27, s25, -1
	s_cmp_eq_u32 s49, 28
	s_cselect_b32 s29, s3, s27
	s_cselect_b32 s28, s14, s26
	s_cselect_b32 s27, s13, s33
	s_cselect_b32 s26, s15, s17
	v_lshl_add_u64 v[198:199], s[24:25], 0, v[132:133]
	s_add_i32 m0, s23, 0xc000
	ds_read_b128 v[204:207], v151
	ds_read_b128 v[208:211], v151 offset:1024
	ds_read_b128 v[212:215], v151 offset:2048
	ds_read_b128 v[226:229], v151 offset:3072
	ds_read_b128 v[230:233], v151 offset:4096
	ds_read_b128 v[234:237], v151 offset:5120
	ds_read_b128 v[238:241], v151 offset:6144
	ds_read_b128 v[242:245], v151 offset:7168
	global_load_lds_dwordx4 v[198:199], off
	v_lshl_add_u64 v[198:199], s[24:25], 0, v[134:135]
	s_add_i32 m0, s23, 0xe000
	s_nop 0
	global_load_lds_dwordx4 v[198:199], off
	s_waitcnt vmcnt(8)
	s_waitcnt lgkmcnt(0)
	s_barrier
	s_setprio 1
	s_waitcnt lgkmcnt(0)
	v_mfma_f32_16x16x32_bf16 v[124:127], v[166:169], v[204:207], v[124:127]
	v_mfma_f32_16x16x32_bf16 v[120:123], v[174:177], v[204:207], v[120:123]
	v_mfma_f32_16x16x32_bf16 v[116:119], v[166:169], v[212:215], v[116:119]
	v_mfma_f32_16x16x32_bf16 v[112:115], v[174:177], v[212:215], v[112:115]
	v_mfma_f32_16x16x32_bf16 v[108:111], v[166:169], v[230:233], v[108:111]
	v_mfma_f32_16x16x32_bf16 v[104:107], v[174:177], v[230:233], v[104:107]
	v_mfma_f32_16x16x32_bf16 v[100:103], v[166:169], v[238:241], v[100:103]
	v_mfma_f32_16x16x32_bf16 v[96:99], v[174:177], v[238:241], v[96:99]
	v_mfma_f32_16x16x32_bf16 v[124:127], v[170:173], v[208:211], v[124:127]
	v_mfma_f32_16x16x32_bf16 v[120:123], v[178:181], v[208:211], v[120:123]
	v_mfma_f32_16x16x32_bf16 v[116:119], v[170:173], v[226:229], v[116:119]
	v_mfma_f32_16x16x32_bf16 v[112:115], v[178:181], v[226:229], v[112:115]
	v_mfma_f32_16x16x32_bf16 v[108:111], v[170:173], v[234:237], v[108:111]
	v_mfma_f32_16x16x32_bf16 v[104:107], v[178:181], v[234:237], v[104:107]
	v_mfma_f32_16x16x32_bf16 v[100:103], v[170:173], v[242:245], v[100:103]
	v_mfma_f32_16x16x32_bf16 v[96:99], v[178:181], v[242:245], v[96:99]
	v_mfma_f32_16x16x32_bf16 v[60:63], v[182:185], v[204:207], v[60:63]
	v_mfma_f32_16x16x32_bf16 v[56:59], v[190:193], v[204:207], v[56:59]
	v_mfma_f32_16x16x32_bf16 v[52:55], v[182:185], v[212:215], v[52:55]
	v_mfma_f32_16x16x32_bf16 v[48:51], v[190:193], v[212:215], v[48:51]
	v_mfma_f32_16x16x32_bf16 v[44:47], v[182:185], v[230:233], v[44:47]
	v_mfma_f32_16x16x32_bf16 v[40:43], v[190:193], v[230:233], v[40:43]
	v_mfma_f32_16x16x32_bf16 v[36:39], v[182:185], v[238:241], v[36:39]
	v_mfma_f32_16x16x32_bf16 v[32:35], v[190:193], v[238:241], v[32:35]
	v_mfma_f32_16x16x32_bf16 v[60:63], v[186:189], v[208:211], v[60:63]
	v_mfma_f32_16x16x32_bf16 v[56:59], v[194:197], v[208:211], v[56:59]
	v_mfma_f32_16x16x32_bf16 v[52:55], v[186:189], v[226:229], v[52:55]
	v_mfma_f32_16x16x32_bf16 v[48:51], v[194:197], v[226:229], v[48:51]
	v_mfma_f32_16x16x32_bf16 v[44:47], v[186:189], v[234:237], v[44:47]
	v_mfma_f32_16x16x32_bf16 v[40:43], v[194:197], v[234:237], v[40:43]
	v_mfma_f32_16x16x32_bf16 v[36:39], v[186:189], v[242:245], v[36:39]
	v_mfma_f32_16x16x32_bf16 v[32:35], v[194:197], v[242:245], v[32:35]
	s_setprio 0
	s_barrier
	s_add_i32 s52, s47, s35
	v_lshl_add_u64 v[198:199], s[26:27], 0, v[156:157]
	s_mov_b32 m0, s52
	ds_read_b128 v[204:207], v151 offset:16384
	ds_read_b128 v[208:211], v151 offset:17408
	ds_read_b128 v[212:215], v151 offset:18432
	ds_read_b128 v[226:229], v151 offset:19456
	ds_read_b128 v[230:233], v151 offset:20480
	ds_read_b128 v[234:237], v151 offset:21504
	ds_read_b128 v[238:241], v151 offset:22528
	ds_read_b128 v[242:245], v151 offset:23552
	global_load_lds_dwordx4 v[198:199], off
	s_add_i32 m0, s52, 0x2000
	s_add_u32 s52, s26, 0x80000
	v_lshl_add_u64 v[216:217], s[26:27], 0, v[160:161]
	s_addc_u32 s53, s27, 0
	s_add_i32 s54, s48, s35
	global_load_lds_dwordx4 v[216:217], off
	v_lshl_add_u64 v[246:247], s[52:53], 0, v[156:157]
	s_mov_b32 m0, s54
	v_lshl_add_u64 v[248:249], s[28:29], 0, v[158:159]
	global_load_lds_dwordx4 v[246:247], off
	v_lshl_add_u64 v[246:247], s[52:53], 0, v[160:161]
	s_add_i32 m0, s54, 0x2000
	s_nop 0
	global_load_lds_dwordx4 v[246:247], off
	v_lshl_add_u64 v[246:247], s[28:29], 0, v[154:155]
	s_mov_b32 m0, s23
	s_nop 0
	global_load_lds_dwordx4 v[246:247], off
	s_mov_b32 m0, s36
	s_nop 0
	global_load_lds_dwordx4 v[248:249], off
	s_waitcnt vmcnt(8)
	s_waitcnt lgkmcnt(0)
	s_barrier
; #define PG8_STAGE(bufoff, gbase, voff) do { _Pragma("unroll") for (int _i = 0; _i < 2; ++_i) \
;         __builtin_amdgcn_global_load_lds((const unsigned*)((const char*)(gbase) + (voff)[_i]), (LAS unsigned*)(lds + (bufoff) + ldsw + _i * 8192), 16, 0, 0); } while (0)
; #define PG8_LDA(dst, b, h) do { _Pragma("unroll") for (int m = 0; m < 4; ++m) _Pragma("unroll") for (int k = 0; k < 2; ++k) dst[m][k] = *(const LAS bf16x8*)(lds + PG8_SA(b, h) + aoff + m * 2048 + k * 1024); } while (0)
; #define PG8_LDB(dst, b, h) do { _Pragma("unroll") for (int n = 0; n < 2; ++n) _Pragma("unroll") for (int k = 0; k < 2; ++k) dst[n][k] = *(const LAS bf16x8*)(lds + PG8_SB(b, h) + boff + n * 2048 + k * 1024); } while (0)
; #define PG8_MMA(ai, bj, At, Bt) do { __builtin_amdgcn_s_setprio(1); _Pragma("unroll") for (int m = 0; m < 4; ++m) _Pragma("unroll") for (int n = 0; n < 2; ++n) _Pragma("unroll") for (int k = 0; k < 2; ++k) \
;         acc[ai][bj][m][n] = __builtin_amdgcn_mfma_f32_16x16x32_bf16(Bt[n][k], At[m][k], acc[ai][bj][m][n], 0, 0, 0); __builtin_amdgcn_s_setprio(0); } while (0)
; #define PG8_WAIT_V(n) asm volatile("s_waitcnt vmcnt(" #n ")" ::: "memory")
; #define PG8_WAIT_L(n) asm volatile("s_waitcnt lgkmcnt(" #n ")" ::: "memory")
; #define PG8_BAR __builtin_amdgcn_s_barrier()
; #define PG8_SCHED __builtin_amdgcn_sched_barrier(0)
; template <class Epi, class Sched>
; __device__ __forceinline__ void gemm_phase(LAS unsigned char* lds, const Gemm g, const Sched& S, const Epi& E) {
;     ...
;             PG8_WAIT_V(8); PG8_WAIT_L(0); PG8_BAR; PG8_MMA(1, 0, At, B0); PG8_MMA(1, 1, At, B1); PG8_BAR; PG8_SCHED;
;             PG8_LDB(B0, 1, 0); PG8_LDB(B1, 1, 1); PG8_SCHED; PG8_LDA(At, 1, 0); PG8_STAGE(PG8_SA(0, 1), a2 + hstep, voffA);
;             PG8_WAIT_V(8); PG8_WAIT_L(0); PG8_BAR; PG8_MMA(0, 0, At, B0); PG8_MMA(0, 1, At, B1); PG8_BAR; PG8_SCHED;
	s_setprio 1
	s_waitcnt lgkmcnt(0)
	v_mfma_f32_16x16x32_bf16 v[92:95], v[166:169], v[204:207], v[92:95]
	v_mfma_f32_16x16x32_bf16 v[88:91], v[174:177], v[204:207], v[88:91]
	v_mfma_f32_16x16x32_bf16 v[84:87], v[166:169], v[212:215], v[84:87]
	v_mfma_f32_16x16x32_bf16 v[80:83], v[174:177], v[212:215], v[80:83]
	v_mfma_f32_16x16x32_bf16 v[76:79], v[166:169], v[230:233], v[76:79]
	v_mfma_f32_16x16x32_bf16 v[72:75], v[174:177], v[230:233], v[72:75]
	v_mfma_f32_16x16x32_bf16 v[68:71], v[166:169], v[238:241], v[68:71]
	v_mfma_f32_16x16x32_bf16 v[64:67], v[174:177], v[238:241], v[64:67]
	v_mfma_f32_16x16x32_bf16 v[92:95], v[170:173], v[208:211], v[92:95]
	v_mfma_f32_16x16x32_bf16 v[88:91], v[178:181], v[208:211], v[88:91]
	v_mfma_f32_16x16x32_bf16 v[84:87], v[170:173], v[226:229], v[84:87]
	v_mfma_f32_16x16x32_bf16 v[80:83], v[178:181], v[226:229], v[80:83]
	v_mfma_f32_16x16x32_bf16 v[76:79], v[170:173], v[234:237], v[76:79]
	v_mfma_f32_16x16x32_bf16 v[72:75], v[178:181], v[234:237], v[72:75]
	v_mfma_f32_16x16x32_bf16 v[68:71], v[170:173], v[242:245], v[68:71]
	v_mfma_f32_16x16x32_bf16 v[64:67], v[178:181], v[242:245], v[64:67]
	v_mfma_f32_16x16x32_bf16 v[28:31], v[182:185], v[204:207], v[28:31]
	v_mfma_f32_16x16x32_bf16 v[24:27], v[190:193], v[204:207], v[24:27]
	v_mfma_f32_16x16x32_bf16 v[20:23], v[182:185], v[212:215], v[20:23]
	v_mfma_f32_16x16x32_bf16 v[16:19], v[190:193], v[212:215], v[16:19]
	v_mfma_f32_16x16x32_bf16 v[12:15], v[182:185], v[230:233], v[12:15]
	v_mfma_f32_16x16x32_bf16 v[8:11], v[190:193], v[230:233], v[8:11]
	v_mfma_f32_16x16x32_bf16 v[4:7], v[182:185], v[238:241], v[4:7]
	v_mfma_f32_16x16x32_bf16 v[0:3], v[190:193], v[238:241], v[0:3]
	v_mfma_f32_16x16x32_bf16 v[28:31], v[186:189], v[208:211], v[28:31]
	v_mfma_f32_16x16x32_bf16 v[24:27], v[194:197], v[208:211], v[24:27]
	v_mfma_f32_16x16x32_bf16 v[20:23], v[186:189], v[226:229], v[20:23]
	v_mfma_f32_16x16x32_bf16 v[16:19], v[194:197], v[226:229], v[16:19]
	v_mfma_f32_16x16x32_bf16 v[12:15], v[186:189], v[234:237], v[12:15]
	v_mfma_f32_16x16x32_bf16 v[8:11], v[194:197], v[234:237], v[8:11]
	v_mfma_f32_16x16x32_bf16 v[4:7], v[186:189], v[242:245], v[4:7]
	v_mfma_f32_16x16x32_bf16 v[0:3], v[194:197], v[242:245], v[0:3]
	s_setprio 0
	s_barrier
	s_add_i32 s52, 0, 0x18000
	v_add_u32_e32 v128, s52, v131
	s_add_i32 s53, 0, 0x1c000
	ds_read_b128 v[166:169], v128
	ds_read_b128 v[170:173], v128 offset:1024
	ds_read_b128 v[174:177], v128 offset:2048
	ds_read_b128 v[178:181], v128 offset:3072
	v_add_u32_e32 v128, s53, v131
	ds_read_b128 v[182:185], v128
	ds_read_b128 v[186:189], v128 offset:1024
	ds_read_b128 v[190:193], v128 offset:2048
	ds_read_b128 v[194:197], v128 offset:3072
	s_add_u32 s28, s28, 0x80000
	s_addc_u32 s29, s29, 0
	s_mov_b32 m0, s37
	v_lshl_add_u64 v[250:251], s[28:29], 0, v[154:155]
	ds_read_b128 v[204:207], v151 offset:32768
	ds_read_b128 v[208:211], v151 offset:33792
	ds_read_b128 v[212:215], v151 offset:34816
	ds_read_b128 v[226:229], v151 offset:35840
	ds_read_b128 v[230:233], v151 offset:36864
	ds_read_b128 v[234:237], v151 offset:37888
	ds_read_b128 v[238:241], v151 offset:38912
	ds_read_b128 v[242:245], v151 offset:39936
	global_load_lds_dwordx4 v[250:251], off
	v_lshl_add_u64 v[250:251], s[28:29], 0, v[158:159]
	s_mov_b32 m0, s38
	s_nop 0
	global_load_lds_dwordx4 v[250:251], off
	s_waitcnt vmcnt(8)
	s_waitcnt lgkmcnt(0)
	s_barrier
	s_setprio 1
	s_waitcnt lgkmcnt(0)
	v_mfma_f32_16x16x32_bf16 v[124:127], v[166:169], v[204:207], v[124:127]
	v_mfma_f32_16x16x32_bf16 v[120:123], v[174:177], v[204:207], v[120:123]
	v_mfma_f32_16x16x32_bf16 v[116:119], v[166:169], v[212:215], v[116:119]
	v_mfma_f32_16x16x32_bf16 v[112:115], v[174:177], v[212:215], v[112:115]
	v_mfma_f32_16x16x32_bf16 v[108:111], v[166:169], v[230:233], v[108:111]
	v_mfma_f32_16x16x32_bf16 v[104:107], v[174:177], v[230:233], v[104:107]
	v_mfma_f32_16x16x32_bf16 v[100:103], v[166:169], v[238:241], v[100:103]
	v_mfma_f32_16x16x32_bf16 v[96:99], v[174:177], v[238:241], v[96:99]
	v_mfma_f32_16x16x32_bf16 v[124:127], v[170:173], v[208:211], v[124:127]
	v_mfma_f32_16x16x32_bf16 v[120:123], v[178:181], v[208:211], v[120:123]
	v_mfma_f32_16x16x32_bf16 v[116:119], v[170:173], v[226:229], v[116:119]
	v_mfma_f32_16x16x32_bf16 v[112:115], v[178:181], v[226:229], v[112:115]
	v_mfma_f32_16x16x32_bf16 v[108:111], v[170:173], v[234:237], v[108:111]
	v_mfma_f32_16x16x32_bf16 v[104:107], v[178:181], v[234:237], v[104:107]
	v_mfma_f32_16x16x32_bf16 v[100:103], v[170:173], v[242:245], v[100:103]
	v_mfma_f32_16x16x32_bf16 v[96:99], v[178:181], v[242:245], v[96:99]
	v_mfma_f32_16x16x32_bf16 v[60:63], v[182:185], v[204:207], v[60:63]
	v_mfma_f32_16x16x32_bf16 v[56:59], v[190:193], v[204:207], v[56:59]
	v_mfma_f32_16x16x32_bf16 v[52:55], v[182:185], v[212:215], v[52:55]
	v_mfma_f32_16x16x32_bf16 v[48:51], v[190:193], v[212:215], v[48:51]
	v_mfma_f32_16x16x32_bf16 v[44:47], v[182:185], v[230:233], v[44:47]
	v_mfma_f32_16x16x32_bf16 v[40:43], v[190:193], v[230:233], v[40:43]
	v_mfma_f32_16x16x32_bf16 v[36:39], v[182:185], v[238:241], v[36:39]
	v_mfma_f32_16x16x32_bf16 v[32:35], v[190:193], v[238:241], v[32:35]
	v_mfma_f32_16x16x32_bf16 v[60:63], v[186:189], v[208:211], v[60:63]
	v_mfma_f32_16x16x32_bf16 v[56:59], v[194:197], v[208:211], v[56:59]
	v_mfma_f32_16x16x32_bf16 v[52:55], v[186:189], v[226:229], v[52:55]
	v_mfma_f32_16x16x32_bf16 v[48:51], v[194:197], v[226:229], v[48:51]
	v_mfma_f32_16x16x32_bf16 v[44:47], v[186:189], v[234:237], v[44:47]
	v_mfma_f32_16x16x32_bf16 v[40:43], v[194:197], v[234:237], v[40:43]
	v_mfma_f32_16x16x32_bf16 v[36:39], v[186:189], v[242:245], v[36:39]
	v_mfma_f32_16x16x32_bf16 v[32:35], v[194:197], v[242:245], v[32:35]
	s_setprio 0
	s_barrier
; #define PG8_STAGE(bufoff, gbase, voff) do { _Pragma("unroll") for (int _i = 0; _i < 2; ++_i) \
;         __builtin_amdgcn_global_load_lds((const unsigned*)((const char*)(gbase) + (voff)[_i]), (LAS unsigned*)(lds + (bufoff) + ldsw + _i * 8192), 16, 0, 0); } while (0)
; #define PG8_LDA(dst, b, h) do { _Pragma("unroll") for (int m = 0; m < 4; ++m) _Pragma("unroll") for (int k = 0; k < 2; ++k) dst[m][k] = *(const LAS bf16x8*)(lds + PG8_SA(b, h) + aoff + m * 2048 + k * 1024); } while (0)
; #define PG8_MMA(ai, bj, At, Bt) do { __builtin_amdgcn_s_setprio(1); _Pragma("unroll") for (int m = 0; m < 4; ++m) _Pragma("unroll") for (int n = 0; n < 2; ++n) _Pragma("unroll") for (int k = 0; k < 2; ++k) \
;         acc[ai][bj][m][n] = __builtin_amdgcn_mfma_f32_16x16x32_bf16(Bt[n][k], At[m][k], acc[ai][bj][m][n], 0, 0, 0); __builtin_amdgcn_s_setprio(0); } while (0)
; #define PG8_WAIT_V(n) asm volatile("s_waitcnt vmcnt(" #n ")" ::: "memory")
; #define PG8_WAIT_L(n) asm volatile("s_waitcnt lgkmcnt(" #n ")" ::: "memory")
; #define PG8_BAR __builtin_amdgcn_s_barrier()
; #define PG8_SCHED __builtin_amdgcn_sched_barrier(0)
; template <class Epi, class Sched>
; __device__ __forceinline__ void gemm_phase(LAS unsigned char* lds, const Gemm g, const Sched& S, const Epi& E) {
;     ...
;             PG8_LDA(At, 1, 1); PG8_STAGE(PG8_SB(1, 0), b3, voffB); PG8_STAGE(PG8_SB(1, 1), b3 + hstep, voffB); PG8_STAGE(PG8_SA(1, 0), a3, voffA);
;             PG8_WAIT_V(8); PG8_WAIT_L(0); PG8_BAR; PG8_MMA(1, 0, At, B0); PG8_MMA(1, 1, At, B1); PG8_BAR; PG8_SCHED;
;         }
	s_add_i32 s28, s52, s35
	v_lshl_add_u64 v[198:199], v[198:199], 0, s[8:9]
	s_mov_b32 m0, s28
	ds_read_b128 v[204:207], v151 offset:49152
	ds_read_b128 v[208:211], v151 offset:50176
	ds_read_b128 v[212:215], v151 offset:51200
	ds_read_b128 v[226:229], v151 offset:52224
	ds_read_b128 v[230:233], v151 offset:53248
	ds_read_b128 v[234:237], v151 offset:54272
	ds_read_b128 v[238:241], v151 offset:55296
	ds_read_b128 v[242:245], v151 offset:56320
	global_load_lds_dwordx4 v[198:199], off
	s_add_i32 m0, s28, 0x2000
	s_add_u32 s26, s26, 0x80080
	v_lshl_add_u64 v[198:199], v[216:217], 0, s[8:9]
	s_addc_u32 s27, s27, 0
	s_add_i32 s28, s53, s35
	global_load_lds_dwordx4 v[198:199], off
	v_lshl_add_u64 v[198:199], s[26:27], 0, v[156:157]
	s_mov_b32 m0, s28
	s_nop 0
	global_load_lds_dwordx4 v[198:199], off
	v_lshl_add_u64 v[198:199], s[26:27], 0, v[160:161]
	s_add_i32 m0, s28, 0x2000
	s_nop 0
	global_load_lds_dwordx4 v[198:199], off
	v_lshl_add_u64 v[198:199], v[246:247], 0, s[8:9]
	s_mov_b32 m0, s41
	s_nop 0
	global_load_lds_dwordx4 v[198:199], off
	v_lshl_add_u64 v[198:199], v[248:249], 0, s[8:9]
	s_mov_b32 m0, s42
	s_nop 0
	global_load_lds_dwordx4 v[198:199], off
	s_waitcnt vmcnt(8)
	s_waitcnt lgkmcnt(0)
	s_barrier
	s_setprio 1
	s_waitcnt lgkmcnt(0)
	v_mfma_f32_16x16x32_bf16 v[92:95], v[166:169], v[204:207], v[92:95]
	v_mfma_f32_16x16x32_bf16 v[88:91], v[174:177], v[204:207], v[88:91]
	v_mfma_f32_16x16x32_bf16 v[84:87], v[166:169], v[212:215], v[84:87]
	v_mfma_f32_16x16x32_bf16 v[80:83], v[174:177], v[212:215], v[80:83]
	v_mfma_f32_16x16x32_bf16 v[76:79], v[166:169], v[230:233], v[76:79]
	v_mfma_f32_16x16x32_bf16 v[72:75], v[174:177], v[230:233], v[72:75]
	v_mfma_f32_16x16x32_bf16 v[68:71], v[166:169], v[238:241], v[68:71]
	v_mfma_f32_16x16x32_bf16 v[64:67], v[174:177], v[238:241], v[64:67]
	v_mfma_f32_16x16x32_bf16 v[92:95], v[170:173], v[208:211], v[92:95]
	v_mfma_f32_16x16x32_bf16 v[88:91], v[178:181], v[208:211], v[88:91]
	v_mfma_f32_16x16x32_bf16 v[84:87], v[170:173], v[226:229], v[84:87]
	v_mfma_f32_16x16x32_bf16 v[80:83], v[178:181], v[226:229], v[80:83]
	v_mfma_f32_16x16x32_bf16 v[76:79], v[170:173], v[234:237], v[76:79]
	v_mfma_f32_16x16x32_bf16 v[72:75], v[178:181], v[234:237], v[72:75]
	v_mfma_f32_16x16x32_bf16 v[68:71], v[170:173], v[242:245], v[68:71]
	v_mfma_f32_16x16x32_bf16 v[64:67], v[178:181], v[242:245], v[64:67]
	v_mfma_f32_16x16x32_bf16 v[28:31], v[182:185], v[204:207], v[28:31]
	v_mfma_f32_16x16x32_bf16 v[24:27], v[190:193], v[204:207], v[24:27]
	v_mfma_f32_16x16x32_bf16 v[20:23], v[182:185], v[212:215], v[20:23]
	v_mfma_f32_16x16x32_bf16 v[16:19], v[190:193], v[212:215], v[16:19]
	v_mfma_f32_16x16x32_bf16 v[12:15], v[182:185], v[230:233], v[12:15]
	v_mfma_f32_16x16x32_bf16 v[8:11], v[190:193], v[230:233], v[8:11]
	v_mfma_f32_16x16x32_bf16 v[4:7], v[182:185], v[238:241], v[4:7]
	v_mfma_f32_16x16x32_bf16 v[0:3], v[190:193], v[238:241], v[0:3]
	v_mfma_f32_16x16x32_bf16 v[28:31], v[186:189], v[208:211], v[28:31]
	v_mfma_f32_16x16x32_bf16 v[24:27], v[194:197], v[208:211], v[24:27]
	v_mfma_f32_16x16x32_bf16 v[20:23], v[186:189], v[226:229], v[20:23]
	v_mfma_f32_16x16x32_bf16 v[16:19], v[194:197], v[226:229], v[16:19]
	v_mfma_f32_16x16x32_bf16 v[12:15], v[186:189], v[234:237], v[12:15]
	v_mfma_f32_16x16x32_bf16 v[8:11], v[194:197], v[234:237], v[8:11]
	v_mfma_f32_16x16x32_bf16 v[4:7], v[186:189], v[242:245], v[4:7]
	v_mfma_f32_16x16x32_bf16 v[0:3], v[194:197], v[242:245], v[0:3]
	s_setprio 0
	s_barrier
	s_add_i32 s49, s49, 2
	s_add_u32 s24, s24, 0x100
	s_addc_u32 s25, s25, 0
	s_add_u32 s17, s17, 0x100
	s_addc_u32 s33, s33, 0
	s_cmp_gt_u32 s49, 29
	s_cbranch_scc0 .LBB0_701
	s_and_b64 vcc, exec, s[10:11]
	s_cbranch_vccz .LBB0_704
	s_barrier

; #define PG8_STAGE(bufoff, gbase, voff) do { _Pragma("unroll") for (int _i = 0; _i < 2; ++_i) \
;         __builtin_amdgcn_global_load_lds((const unsigned*)((const char*)(gbase) + (voff)[_i]), (LAS unsigned*)(lds + (bufoff) + ldsw + _i * 8192), 16, 0, 0); } while (0)
; #define PG8_LDA(dst, b, h) do { _Pragma("unroll") for (int m = 0; m < 4; ++m) _Pragma("unroll") for (int k = 0; k < 2; ++k) dst[m][k] = *(const LAS bf16x8*)(lds + PG8_SA(b, h) + aoff + m * 2048 + k * 1024); } while (0)
; #define PG8_LDB(dst, b, h) do { _Pragma("unroll") for (int n = 0; n < 2; ++n) _Pragma("unroll") for (int k = 0; k < 2; ++k) dst[n][k] = *(const LAS bf16x8*)(lds + PG8_SB(b, h) + boff + n * 2048 + k * 1024); } while (0)
; #define PG8_MMA(ai, bj, At, Bt) do { __builtin_amdgcn_s_setprio(1); _Pragma("unroll") for (int m = 0; m < 4; ++m) _Pragma("unroll") for (int n = 0; n < 2; ++n) _Pragma("unroll") for (int k = 0; k < 2; ++k) \
;         acc[ai][bj][m][n] = __builtin_amdgcn_mfma_f32_16x16x32_bf16(Bt[n][k], At[m][k], acc[ai][bj][m][n], 0, 0, 0); __builtin_amdgcn_s_setprio(0); } while (0)
; #define PG8_WAIT_V(n) asm volatile("s_waitcnt vmcnt(" #n ")" ::: "memory")
; #define PG8_WAIT_L(n) asm volatile("s_waitcnt lgkmcnt(" #n ")" ::: "memory")
; #define PG8_BAR __builtin_amdgcn_s_barrier()
; #define PG8_SCHED __builtin_amdgcn_sched_barrier(0)
; template <class Epi, class Sched>
; __device__ __forceinline__ void gemm_phase(LAS unsigned char* lds, const Gemm g, const Sched& S, const Epi& E) {
;     ...
;         for (int t = 0; t < nt; t += 2) {
;             const bool last = (t == nt - 2);
;             const char* a1 = cA + (size_t)(t + 1) * kstep;
;             const char* a2 = last ? nA : cA + (size_t)(t + 2) * kstep; const char* b2 = last ? nB : cB + (size_t)(t + 2) * kstep;
;             const char* a3 = a2 + kstep; const char* b3 = b2 + kstep;
;             PG8_LDB(B0, 0, 0); PG8_LDB(B1, 0, 1); PG8_SCHED; PG8_LDA(At, 0, 0); PG8_STAGE(PG8_SA(1, 1), a1 + hstep, voffA);
;             PG8_WAIT_V(8); PG8_WAIT_L(0); PG8_BAR; PG8_MMA(0, 0, At, B0); PG8_MMA(0, 1, At, B1); PG8_BAR; PG8_SCHED;
;             PG8_LDA(At, 0, 1); PG8_STAGE(PG8_SB(0, 0), b2, voffB); PG8_STAGE(PG8_SB(0, 1), b2 + hstep, voffB); PG8_STAGE(PG8_SA(0, 0), a2, voffA);
.LBB0_863:
	ds_read_b128 v[120:123], v200
	ds_read_b128 v[124:127], v200 offset:1024
	ds_read_b128 v[136:139], v200 offset:2048
	ds_read_b128 v[140:143], v200 offset:3072
	ds_read_b128 v[144:147], v201
	ds_read_b128 v[148:151], v201 offset:1024
	ds_read_b128 v[174:177], v201 offset:2048
	ds_read_b128 v[178:181], v201 offset:3072
	s_add_u32 s24, s22, 0xfff80080
	s_addc_u32 s25, s23, -1
	s_cmp_eq_u32 s46, 28
	s_cselect_b32 s27, s13, s25
	s_cselect_b32 s26, s14, s24
	s_cselect_b32 s25, s11, s43
	s_cselect_b32 s24, s15, s33
	v_lshl_add_u64 v[216:217], s[22:23], 0, v[166:167]
	s_add_i32 m0, s21, 0xc000
	ds_read_b128 v[182:185], v202
	ds_read_b128 v[186:189], v202 offset:1024
	ds_read_b128 v[190:193], v202 offset:2048
	ds_read_b128 v[194:197], v202 offset:3072
	ds_read_b128 v[204:207], v202 offset:4096
	ds_read_b128 v[208:211], v202 offset:5120
	ds_read_b128 v[212:215], v202 offset:6144
	ds_read_b128 v[226:229], v202 offset:7168
	global_load_lds_dwordx4 v[216:217], off
	v_lshl_add_u64 v[216:217], s[22:23], 0, v[168:169]
	s_add_i32 m0, s21, 0xe000
	s_nop 0
	global_load_lds_dwordx4 v[216:217], off
	s_waitcnt vmcnt(8)
	s_waitcnt lgkmcnt(0)
	s_barrier
	s_setprio 1
	s_waitcnt lgkmcnt(0)
	v_mfma_f32_16x16x32_bf16 v[132:135], v[120:123], v[182:185], v[132:135]
	v_mfma_f32_16x16x32_bf16 v[128:131], v[136:139], v[182:185], v[128:131]
	v_mfma_f32_16x16x32_bf16 v[116:119], v[120:123], v[190:193], v[116:119]
	v_mfma_f32_16x16x32_bf16 v[112:115], v[136:139], v[190:193], v[112:115]
	v_mfma_f32_16x16x32_bf16 v[108:111], v[120:123], v[204:207], v[108:111]
	v_mfma_f32_16x16x32_bf16 v[104:107], v[136:139], v[204:207], v[104:107]
	v_mfma_f32_16x16x32_bf16 v[100:103], v[120:123], v[212:215], v[100:103]
	v_mfma_f32_16x16x32_bf16 v[96:99], v[136:139], v[212:215], v[96:99]
	v_mfma_f32_16x16x32_bf16 v[132:135], v[124:127], v[186:189], v[132:135]
	v_mfma_f32_16x16x32_bf16 v[128:131], v[140:143], v[186:189], v[128:131]
	v_mfma_f32_16x16x32_bf16 v[116:119], v[124:127], v[194:197], v[116:119]
	v_mfma_f32_16x16x32_bf16 v[112:115], v[140:143], v[194:197], v[112:115]
	v_mfma_f32_16x16x32_bf16 v[108:111], v[124:127], v[208:211], v[108:111]
	v_mfma_f32_16x16x32_bf16 v[104:107], v[140:143], v[208:211], v[104:107]
	v_mfma_f32_16x16x32_bf16 v[100:103], v[124:127], v[226:229], v[100:103]
	v_mfma_f32_16x16x32_bf16 v[96:99], v[140:143], v[226:229], v[96:99]
	v_mfma_f32_16x16x32_bf16 v[60:63], v[144:147], v[182:185], v[60:63]
	v_mfma_f32_16x16x32_bf16 v[56:59], v[174:177], v[182:185], v[56:59]
	v_mfma_f32_16x16x32_bf16 v[52:55], v[144:147], v[190:193], v[52:55]
	v_mfma_f32_16x16x32_bf16 v[48:51], v[174:177], v[190:193], v[48:51]
	v_mfma_f32_16x16x32_bf16 v[44:47], v[144:147], v[204:207], v[44:47]
	v_mfma_f32_16x16x32_bf16 v[40:43], v[174:177], v[204:207], v[40:43]
	v_mfma_f32_16x16x32_bf16 v[36:39], v[144:147], v[212:215], v[36:39]
	v_mfma_f32_16x16x32_bf16 v[32:35], v[174:177], v[212:215], v[32:35]
	v_mfma_f32_16x16x32_bf16 v[60:63], v[148:151], v[186:189], v[60:63]
	v_mfma_f32_16x16x32_bf16 v[56:59], v[178:181], v[186:189], v[56:59]
	v_mfma_f32_16x16x32_bf16 v[52:55], v[148:151], v[194:197], v[52:55]
	v_mfma_f32_16x16x32_bf16 v[48:51], v[178:181], v[194:197], v[48:51]
	v_mfma_f32_16x16x32_bf16 v[44:47], v[148:151], v[208:211], v[44:47]
	v_mfma_f32_16x16x32_bf16 v[40:43], v[178:181], v[208:211], v[40:43]
	v_mfma_f32_16x16x32_bf16 v[36:39], v[148:151], v[226:229], v[36:39]
	v_mfma_f32_16x16x32_bf16 v[32:35], v[178:181], v[226:229], v[32:35]
	s_setprio 0
	s_barrier
	s_add_i32 s47, s41, s30
	v_lshl_add_u64 v[216:217], s[24:25], 0, v[156:157]
	s_mov_b32 m0, s47
	ds_read_b128 v[182:185], v202 offset:16384
	ds_read_b128 v[186:189], v202 offset:17408
	ds_read_b128 v[190:193], v202 offset:18432
	ds_read_b128 v[194:197], v202 offset:19456
	ds_read_b128 v[204:207], v202 offset:20480
	ds_read_b128 v[208:211], v202 offset:21504
	ds_read_b128 v[212:215], v202 offset:22528
	ds_read_b128 v[226:229], v202 offset:23552
	global_load_lds_dwordx4 v[216:217], off
	s_add_i32 m0, s47, 0x2000
	s_add_u32 s48, s24, 0x80000
	v_lshl_add_u64 v[230:231], s[24:25], 0, v[160:161]
	s_addc_u32 s49, s25, 0
	s_add_i32 s47, s42, s30
	global_load_lds_dwordx4 v[230:231], off
	v_lshl_add_u64 v[232:233], s[48:49], 0, v[156:157]
	s_mov_b32 m0, s47
	v_lshl_add_u64 v[234:235], s[26:27], 0, v[158:159]
	global_load_lds_dwordx4 v[232:233], off
	v_lshl_add_u64 v[232:233], s[48:49], 0, v[160:161]
	s_add_i32 m0, s47, 0x2000
	s_nop 0
	global_load_lds_dwordx4 v[232:233], off
	v_lshl_add_u64 v[232:233], s[26:27], 0, v[154:155]
	s_mov_b32 m0, s21
	s_nop 0
	global_load_lds_dwordx4 v[232:233], off
	s_mov_b32 m0, s31
	s_nop 0
	global_load_lds_dwordx4 v[234:235], off
	s_waitcnt vmcnt(8)
	s_waitcnt lgkmcnt(0)
	s_barrier
; #define PG8_STAGE(bufoff, gbase, voff) do { _Pragma("unroll") for (int _i = 0; _i < 2; ++_i) \
;         __builtin_amdgcn_global_load_lds((const unsigned*)((const char*)(gbase) + (voff)[_i]), (LAS unsigned*)(lds + (bufoff) + ldsw + _i * 8192), 16, 0, 0); } while (0)
; #define PG8_LDA(dst, b, h) do { _Pragma("unroll") for (int m = 0; m < 4; ++m) _Pragma("unroll") for (int k = 0; k < 2; ++k) dst[m][k] = *(const LAS bf16x8*)(lds + PG8_SA(b, h) + aoff + m * 2048 + k * 1024); } while (0)
; #define PG8_LDB(dst, b, h) do { _Pragma("unroll") for (int n = 0; n < 2; ++n) _Pragma("unroll") for (int k = 0; k < 2; ++k) dst[n][k] = *(const LAS bf16x8*)(lds + PG8_SB(b, h) + boff + n * 2048 + k * 1024); } while (0)
; #define PG8_MMA(ai, bj, At, Bt) do { __builtin_amdgcn_s_setprio(1); _Pragma("unroll") for (int m = 0; m < 4; ++m) _Pragma("unroll") for (int n = 0; n < 2; ++n) _Pragma("unroll") for (int k = 0; k < 2; ++k) \
;         acc[ai][bj][m][n] = __builtin_amdgcn_mfma_f32_16x16x32_bf16(Bt[n][k], At[m][k], acc[ai][bj][m][n], 0, 0, 0); __builtin_amdgcn_s_setprio(0); } while (0)
; #define PG8_WAIT_V(n) asm volatile("s_waitcnt vmcnt(" #n ")" ::: "memory")
; #define PG8_WAIT_L(n) asm volatile("s_waitcnt lgkmcnt(" #n ")" ::: "memory")
; #define PG8_BAR __builtin_amdgcn_s_barrier()
; #define PG8_SCHED __builtin_amdgcn_sched_barrier(0)
; template <class Epi, class Sched>
; __device__ __forceinline__ void gemm_phase(LAS unsigned char* lds, const Gemm g, const Sched& S, const Epi& E) {
;     ...
;             PG8_WAIT_V(8); PG8_WAIT_L(0); PG8_BAR; PG8_MMA(1, 0, At, B0); PG8_MMA(1, 1, At, B1); PG8_BAR; PG8_SCHED;
;             PG8_LDB(B0, 1, 0); PG8_LDB(B1, 1, 1); PG8_SCHED; PG8_LDA(At, 1, 0); PG8_STAGE(PG8_SA(0, 1), a2 + hstep, voffA);
;             PG8_WAIT_V(8); PG8_WAIT_L(0); PG8_BAR; PG8_MMA(0, 0, At, B0); PG8_MMA(0, 1, At, B1); PG8_BAR; PG8_SCHED;
	s_setprio 1
	s_waitcnt lgkmcnt(0)
	v_mfma_f32_16x16x32_bf16 v[92:95], v[120:123], v[182:185], v[92:95]
	v_mfma_f32_16x16x32_bf16 v[88:91], v[136:139], v[182:185], v[88:91]
	v_mfma_f32_16x16x32_bf16 v[84:87], v[120:123], v[190:193], v[84:87]
	v_mfma_f32_16x16x32_bf16 v[80:83], v[136:139], v[190:193], v[80:83]
	v_mfma_f32_16x16x32_bf16 v[76:79], v[120:123], v[204:207], v[76:79]
	v_mfma_f32_16x16x32_bf16 v[72:75], v[136:139], v[204:207], v[72:75]
	v_mfma_f32_16x16x32_bf16 v[68:71], v[120:123], v[212:215], v[68:71]
	v_mfma_f32_16x16x32_bf16 v[64:67], v[136:139], v[212:215], v[64:67]
	v_mfma_f32_16x16x32_bf16 v[92:95], v[124:127], v[186:189], v[92:95]
	v_mfma_f32_16x16x32_bf16 v[88:91], v[140:143], v[186:189], v[88:91]
	v_mfma_f32_16x16x32_bf16 v[84:87], v[124:127], v[194:197], v[84:87]
	v_mfma_f32_16x16x32_bf16 v[80:83], v[140:143], v[194:197], v[80:83]
	v_mfma_f32_16x16x32_bf16 v[76:79], v[124:127], v[208:211], v[76:79]
	v_mfma_f32_16x16x32_bf16 v[72:75], v[140:143], v[208:211], v[72:75]
	v_mfma_f32_16x16x32_bf16 v[68:71], v[124:127], v[226:229], v[68:71]
	v_mfma_f32_16x16x32_bf16 v[64:67], v[140:143], v[226:229], v[64:67]
	v_mfma_f32_16x16x32_bf16 v[28:31], v[144:147], v[182:185], v[28:31]
	v_mfma_f32_16x16x32_bf16 v[24:27], v[174:177], v[182:185], v[24:27]
	v_mfma_f32_16x16x32_bf16 v[20:23], v[144:147], v[190:193], v[20:23]
	v_mfma_f32_16x16x32_bf16 v[16:19], v[174:177], v[190:193], v[16:19]
	v_mfma_f32_16x16x32_bf16 v[12:15], v[144:147], v[204:207], v[12:15]
	v_mfma_f32_16x16x32_bf16 v[8:11], v[174:177], v[204:207], v[8:11]
	v_mfma_f32_16x16x32_bf16 v[4:7], v[144:147], v[212:215], v[4:7]
	v_mfma_f32_16x16x32_bf16 v[0:3], v[174:177], v[212:215], v[0:3]
	v_mfma_f32_16x16x32_bf16 v[28:31], v[148:151], v[186:189], v[28:31]
	v_mfma_f32_16x16x32_bf16 v[24:27], v[178:181], v[186:189], v[24:27]
	v_mfma_f32_16x16x32_bf16 v[20:23], v[148:151], v[194:197], v[20:23]
	v_mfma_f32_16x16x32_bf16 v[16:19], v[178:181], v[194:197], v[16:19]
	v_mfma_f32_16x16x32_bf16 v[12:15], v[148:151], v[208:211], v[12:15]
	v_mfma_f32_16x16x32_bf16 v[8:11], v[178:181], v[208:211], v[8:11]
	v_mfma_f32_16x16x32_bf16 v[4:7], v[148:151], v[226:229], v[4:7]
	v_mfma_f32_16x16x32_bf16 v[0:3], v[178:181], v[226:229], v[0:3]
	s_setprio 0
	s_barrier
	s_add_i32 s47, 0, 0x18000
	s_add_i32 s48, 0, 0x1c000
	v_add_u32_e32 v140, s47, v198
	v_add_u32_e32 v178, s48, v198
	ds_read_b128 v[120:123], v140
	ds_read_b128 v[124:127], v140 offset:1024
	ds_read_b128 v[136:139], v140 offset:2048
	ds_read_b128 v[140:143], v140 offset:3072
	ds_read_b128 v[144:147], v178
	ds_read_b128 v[148:151], v178 offset:1024
	ds_read_b128 v[174:177], v178 offset:2048
	ds_read_b128 v[178:181], v178 offset:3072
	s_add_u32 s26, s26, 0x80000
	s_addc_u32 s27, s27, 0
	s_mov_b32 m0, s34
	v_lshl_add_u64 v[236:237], s[26:27], 0, v[154:155]
	ds_read_b128 v[182:185], v202 offset:32768
	ds_read_b128 v[186:189], v202 offset:33792
	ds_read_b128 v[190:193], v202 offset:34816
	ds_read_b128 v[194:197], v202 offset:35840
	ds_read_b128 v[204:207], v202 offset:36864
	ds_read_b128 v[208:211], v202 offset:37888
	ds_read_b128 v[212:215], v202 offset:38912
	ds_read_b128 v[226:229], v202 offset:39936
	global_load_lds_dwordx4 v[236:237], off
	v_lshl_add_u64 v[236:237], s[26:27], 0, v[158:159]
	s_mov_b32 m0, s35
	s_nop 0
	global_load_lds_dwordx4 v[236:237], off
	s_waitcnt vmcnt(8)
	s_waitcnt lgkmcnt(0)
	s_barrier
	s_setprio 1
	s_waitcnt lgkmcnt(0)
	v_mfma_f32_16x16x32_bf16 v[132:135], v[120:123], v[182:185], v[132:135]
	v_mfma_f32_16x16x32_bf16 v[128:131], v[136:139], v[182:185], v[128:131]
	v_mfma_f32_16x16x32_bf16 v[116:119], v[120:123], v[190:193], v[116:119]
	v_mfma_f32_16x16x32_bf16 v[112:115], v[136:139], v[190:193], v[112:115]
	v_mfma_f32_16x16x32_bf16 v[108:111], v[120:123], v[204:207], v[108:111]
	v_mfma_f32_16x16x32_bf16 v[104:107], v[136:139], v[204:207], v[104:107]
	v_mfma_f32_16x16x32_bf16 v[100:103], v[120:123], v[212:215], v[100:103]
	v_mfma_f32_16x16x32_bf16 v[96:99], v[136:139], v[212:215], v[96:99]
	v_mfma_f32_16x16x32_bf16 v[132:135], v[124:127], v[186:189], v[132:135]
	v_mfma_f32_16x16x32_bf16 v[128:131], v[140:143], v[186:189], v[128:131]
	v_mfma_f32_16x16x32_bf16 v[116:119], v[124:127], v[194:197], v[116:119]
	v_mfma_f32_16x16x32_bf16 v[112:115], v[140:143], v[194:197], v[112:115]
	v_mfma_f32_16x16x32_bf16 v[108:111], v[124:127], v[208:211], v[108:111]
	v_mfma_f32_16x16x32_bf16 v[104:107], v[140:143], v[208:211], v[104:107]
	v_mfma_f32_16x16x32_bf16 v[100:103], v[124:127], v[226:229], v[100:103]
	v_mfma_f32_16x16x32_bf16 v[96:99], v[140:143], v[226:229], v[96:99]
	v_mfma_f32_16x16x32_bf16 v[60:63], v[144:147], v[182:185], v[60:63]
	v_mfma_f32_16x16x32_bf16 v[56:59], v[174:177], v[182:185], v[56:59]
	v_mfma_f32_16x16x32_bf16 v[52:55], v[144:147], v[190:193], v[52:55]
	v_mfma_f32_16x16x32_bf16 v[48:51], v[174:177], v[190:193], v[48:51]
	v_mfma_f32_16x16x32_bf16 v[44:47], v[144:147], v[204:207], v[44:47]
	v_mfma_f32_16x16x32_bf16 v[40:43], v[174:177], v[204:207], v[40:43]
	v_mfma_f32_16x16x32_bf16 v[36:39], v[144:147], v[212:215], v[36:39]
	v_mfma_f32_16x16x32_bf16 v[32:35], v[174:177], v[212:215], v[32:35]
	v_mfma_f32_16x16x32_bf16 v[60:63], v[148:151], v[186:189], v[60:63]
	v_mfma_f32_16x16x32_bf16 v[56:59], v[178:181], v[186:189], v[56:59]
	v_mfma_f32_16x16x32_bf16 v[52:55], v[148:151], v[194:197], v[52:55]
	v_mfma_f32_16x16x32_bf16 v[48:51], v[178:181], v[194:197], v[48:51]
	v_mfma_f32_16x16x32_bf16 v[44:47], v[148:151], v[208:211], v[44:47]
	v_mfma_f32_16x16x32_bf16 v[40:43], v[178:181], v[208:211], v[40:43]
	v_mfma_f32_16x16x32_bf16 v[36:39], v[148:151], v[226:229], v[36:39]
	v_mfma_f32_16x16x32_bf16 v[32:35], v[178:181], v[226:229], v[32:35]
	s_setprio 0
	s_barrier
; #define PG8_STAGE(bufoff, gbase, voff) do { _Pragma("unroll") for (int _i = 0; _i < 2; ++_i) \
;         __builtin_amdgcn_global_load_lds((const unsigned*)((const char*)(gbase) + (voff)[_i]), (LAS unsigned*)(lds + (bufoff) + ldsw + _i * 8192), 16, 0, 0); } while (0)
; #define PG8_LDA(dst, b, h) do { _Pragma("unroll") for (int m = 0; m < 4; ++m) _Pragma("unroll") for (int k = 0; k < 2; ++k) dst[m][k] = *(const LAS bf16x8*)(lds + PG8_SA(b, h) + aoff + m * 2048 + k * 1024); } while (0)
; #define PG8_MMA(ai, bj, At, Bt) do { __builtin_amdgcn_s_setprio(1); _Pragma("unroll") for (int m = 0; m < 4; ++m) _Pragma("unroll") for (int n = 0; n < 2; ++n) _Pragma("unroll") for (int k = 0; k < 2; ++k) \
;         acc[ai][bj][m][n] = __builtin_amdgcn_mfma_f32_16x16x32_bf16(Bt[n][k], At[m][k], acc[ai][bj][m][n], 0, 0, 0); __builtin_amdgcn_s_setprio(0); } while (0)
; #define PG8_WAIT_V(n) asm volatile("s_waitcnt vmcnt(" #n ")" ::: "memory")
; #define PG8_WAIT_L(n) asm volatile("s_waitcnt lgkmcnt(" #n ")" ::: "memory")
; #define PG8_BAR __builtin_amdgcn_s_barrier()
; #define PG8_SCHED __builtin_amdgcn_sched_barrier(0)
; template <class Epi, class Sched>
; __device__ __forceinline__ void gemm_phase(LAS unsigned char* lds, const Gemm g, const Sched& S, const Epi& E) {
;     ...
;             PG8_LDA(At, 1, 1); PG8_STAGE(PG8_SB(1, 0), b3, voffB); PG8_STAGE(PG8_SB(1, 1), b3 + hstep, voffB); PG8_STAGE(PG8_SA(1, 0), a3, voffA);
;             PG8_WAIT_V(8); PG8_WAIT_L(0); PG8_BAR; PG8_MMA(1, 0, At, B0); PG8_MMA(1, 1, At, B1); PG8_BAR; PG8_SCHED;
;         }
	s_add_i32 s26, s47, s30
	v_lshl_add_u64 v[216:217], v[216:217], 0, s[6:7]
	s_mov_b32 m0, s26
	ds_read_b128 v[182:185], v202 offset:49152
	ds_read_b128 v[186:189], v202 offset:50176
	ds_read_b128 v[190:193], v202 offset:51200
	ds_read_b128 v[194:197], v202 offset:52224
	ds_read_b128 v[204:207], v202 offset:53248
	ds_read_b128 v[208:211], v202 offset:54272
	ds_read_b128 v[212:215], v202 offset:55296
	ds_read_b128 v[226:229], v202 offset:56320
	global_load_lds_dwordx4 v[216:217], off
	s_add_i32 m0, s26, 0x2000
	s_add_u32 s24, s24, 0x80080
	v_lshl_add_u64 v[216:217], v[230:231], 0, s[6:7]
	s_addc_u32 s25, s25, 0
	s_add_i32 s26, s48, s30
	global_load_lds_dwordx4 v[216:217], off
	v_lshl_add_u64 v[216:217], s[24:25], 0, v[156:157]
	s_mov_b32 m0, s26
	s_nop 0
	global_load_lds_dwordx4 v[216:217], off
	v_lshl_add_u64 v[216:217], s[24:25], 0, v[160:161]
	s_add_i32 m0, s26, 0x2000
	s_nop 0
	global_load_lds_dwordx4 v[216:217], off
	v_lshl_add_u64 v[216:217], v[232:233], 0, s[6:7]
	s_mov_b32 m0, s37
	s_nop 0
	global_load_lds_dwordx4 v[216:217], off
	v_lshl_add_u64 v[216:217], v[234:235], 0, s[6:7]
	s_mov_b32 m0, s38
	s_nop 0
	global_load_lds_dwordx4 v[216:217], off
	s_waitcnt vmcnt(8)
	s_waitcnt lgkmcnt(0)
	s_barrier
	s_setprio 1
	s_waitcnt lgkmcnt(0)
	v_mfma_f32_16x16x32_bf16 v[92:95], v[120:123], v[182:185], v[92:95]
	v_mfma_f32_16x16x32_bf16 v[88:91], v[136:139], v[182:185], v[88:91]
	v_mfma_f32_16x16x32_bf16 v[84:87], v[120:123], v[190:193], v[84:87]
	v_mfma_f32_16x16x32_bf16 v[80:83], v[136:139], v[190:193], v[80:83]
	v_mfma_f32_16x16x32_bf16 v[76:79], v[120:123], v[204:207], v[76:79]
	v_mfma_f32_16x16x32_bf16 v[72:75], v[136:139], v[204:207], v[72:75]
	v_mfma_f32_16x16x32_bf16 v[68:71], v[120:123], v[212:215], v[68:71]
	v_mfma_f32_16x16x32_bf16 v[64:67], v[136:139], v[212:215], v[64:67]
	v_mfma_f32_16x16x32_bf16 v[92:95], v[124:127], v[186:189], v[92:95]
	v_mfma_f32_16x16x32_bf16 v[88:91], v[140:143], v[186:189], v[88:91]
	v_mfma_f32_16x16x32_bf16 v[84:87], v[124:127], v[194:197], v[84:87]
	v_mfma_f32_16x16x32_bf16 v[80:83], v[140:143], v[194:197], v[80:83]
	v_mfma_f32_16x16x32_bf16 v[76:79], v[124:127], v[208:211], v[76:79]
	v_mfma_f32_16x16x32_bf16 v[72:75], v[140:143], v[208:211], v[72:75]
	v_mfma_f32_16x16x32_bf16 v[68:71], v[124:127], v[226:229], v[68:71]
	v_mfma_f32_16x16x32_bf16 v[64:67], v[140:143], v[226:229], v[64:67]
	v_mfma_f32_16x16x32_bf16 v[28:31], v[144:147], v[182:185], v[28:31]
	v_mfma_f32_16x16x32_bf16 v[24:27], v[174:177], v[182:185], v[24:27]
	v_mfma_f32_16x16x32_bf16 v[20:23], v[144:147], v[190:193], v[20:23]
	v_mfma_f32_16x16x32_bf16 v[16:19], v[174:177], v[190:193], v[16:19]
	v_mfma_f32_16x16x32_bf16 v[12:15], v[144:147], v[204:207], v[12:15]
	v_mfma_f32_16x16x32_bf16 v[8:11], v[174:177], v[204:207], v[8:11]
	v_mfma_f32_16x16x32_bf16 v[4:7], v[144:147], v[212:215], v[4:7]
	v_mfma_f32_16x16x32_bf16 v[0:3], v[174:177], v[212:215], v[0:3]
	v_mfma_f32_16x16x32_bf16 v[28:31], v[148:151], v[186:189], v[28:31]
	v_mfma_f32_16x16x32_bf16 v[24:27], v[178:181], v[186:189], v[24:27]
	v_mfma_f32_16x16x32_bf16 v[20:23], v[148:151], v[194:197], v[20:23]
	v_mfma_f32_16x16x32_bf16 v[16:19], v[178:181], v[194:197], v[16:19]
	v_mfma_f32_16x16x32_bf16 v[12:15], v[148:151], v[208:211], v[12:15]
	v_mfma_f32_16x16x32_bf16 v[8:11], v[178:181], v[208:211], v[8:11]
	v_mfma_f32_16x16x32_bf16 v[4:7], v[148:151], v[226:229], v[4:7]
	v_mfma_f32_16x16x32_bf16 v[0:3], v[178:181], v[226:229], v[0:3]
	s_setprio 0
	s_barrier
	s_add_i32 s46, s46, 2
	s_add_u32 s22, s22, 0x100
	s_addc_u32 s23, s23, 0
	s_add_u32 s33, s33, 0x100
	s_addc_u32 s43, s43, 0
	s_cmp_gt_u32 s46, 29
	s_cbranch_scc0 .LBB0_863
	s_and_b64 vcc, exec, s[8:9]
	s_cbranch_vccz .LBB0_866
	s_barrier

; #define PG8_STAGE(bufoff, gbase, voff) do { _Pragma("unroll") for (int _i = 0; _i < 2; ++_i) \
;         __builtin_amdgcn_global_load_lds((const unsigned*)((const char*)(gbase) + (voff)[_i]), (LAS unsigned*)(lds + (bufoff) + ldsw + _i * 8192), 16, 0, 0); } while (0)
; #define PG8_LDA(dst, b, h) do { _Pragma("unroll") for (int m = 0; m < 4; ++m) _Pragma("unroll") for (int k = 0; k < 2; ++k) dst[m][k] = *(const LAS bf16x8*)(lds + PG8_SA(b, h) + aoff + m * 2048 + k * 1024); } while (0)
; #define PG8_LDB(dst, b, h) do { _Pragma("unroll") for (int n = 0; n < 2; ++n) _Pragma("unroll") for (int k = 0; k < 2; ++k) dst[n][k] = *(const LAS bf16x8*)(lds + PG8_SB(b, h) + boff + n * 2048 + k * 1024); } while (0)
; #define PG8_MMA(ai, bj, At, Bt) do { __builtin_amdgcn_s_setprio(1); _Pragma("unroll") for (int m = 0; m < 4; ++m) _Pragma("unroll") for (int n = 0; n < 2; ++n) _Pragma("unroll") for (int k = 0; k < 2; ++k) \
;         acc[ai][bj][m][n] = __builtin_amdgcn_mfma_f32_16x16x32_bf16(Bt[n][k], At[m][k], acc[ai][bj][m][n], 0, 0, 0); __builtin_amdgcn_s_setprio(0); } while (0)
; #define PG8_WAIT_V(n) asm volatile("s_waitcnt vmcnt(" #n ")" ::: "memory")
; #define PG8_WAIT_L(n) asm volatile("s_waitcnt lgkmcnt(" #n ")" ::: "memory")
; #define PG8_BAR __builtin_amdgcn_s_barrier()
; #define PG8_SCHED __builtin_amdgcn_sched_barrier(0)
; template <class Epi, class Sched>
; __device__ __forceinline__ void gemm_phase(LAS unsigned char* lds, const Gemm g, const Sched& S, const Epi& E) {
;     ...
;         for (int t = 0; t < nt; t += 2) {
;             const bool last = (t == nt - 2);
;             const char* a1 = cA + (size_t)(t + 1) * kstep;
;             const char* a2 = last ? nA : cA + (size_t)(t + 2) * kstep; const char* b2 = last ? nB : cB + (size_t)(t + 2) * kstep;
;             const char* a3 = a2 + kstep; const char* b3 = b2 + kstep;
;             PG8_LDB(B0, 0, 0); PG8_LDB(B1, 0, 1); PG8_SCHED; PG8_LDA(At, 0, 0); PG8_STAGE(PG8_SA(1, 1), a1 + hstep, voffA);
;             PG8_WAIT_V(8); PG8_WAIT_L(0); PG8_BAR; PG8_MMA(0, 0, At, B0); PG8_MMA(0, 1, At, B1); PG8_BAR; PG8_SCHED;
;             PG8_LDA(At, 0, 1); PG8_STAGE(PG8_SB(0, 0), b2, voffB); PG8_STAGE(PG8_SB(0, 1), b2 + hstep, voffB); PG8_STAGE(PG8_SA(0, 0), a2, voffA);
.LBB0_939:
	ds_read_b128 v[136:139], v149
	ds_read_b128 v[140:143], v149 offset:1024
	ds_read_b128 v[164:167], v149 offset:2048
	ds_read_b128 v[168:171], v149 offset:3072
	ds_read_b128 v[172:175], v150
	ds_read_b128 v[176:179], v150 offset:1024
	ds_read_b128 v[180:183], v150 offset:2048
	ds_read_b128 v[184:187], v150 offset:3072
	s_add_u32 s34, s30, 0xfff80080
	s_addc_u32 s35, s31, -1
	s_cmp_eq_u32 s58, 28
	s_cselect_b32 s37, s14, s35
	s_cselect_b32 s36, s15, s34
	s_cselect_b32 s35, s21, s55
	s_cselect_b32 s34, s23, s33
	v_lshl_add_u64 v[144:145], s[30:31], 0, v[128:129]
	s_add_i32 m0, s29, 0xc000
	ds_read_b128 v[188:191], v151
	ds_read_b128 v[192:195], v151 offset:1024
	ds_read_b128 v[196:199], v151 offset:2048
	ds_read_b128 v[200:203], v151 offset:3072
	ds_read_b128 v[204:207], v151 offset:4096
	ds_read_b128 v[208:211], v151 offset:5120
	ds_read_b128 v[212:215], v151 offset:6144
	ds_read_b128 v[216:219], v151 offset:7168
	global_load_lds_dwordx4 v[144:145], off
	v_lshl_add_u64 v[144:145], s[30:31], 0, v[130:131]
	s_add_i32 m0, s29, 0xe000
	s_nop 0
	global_load_lds_dwordx4 v[144:145], off
	s_waitcnt vmcnt(8)
	s_waitcnt lgkmcnt(0)
	s_barrier
	s_setprio 1
	s_waitcnt lgkmcnt(0)
	v_mfma_f32_16x16x32_bf16 v[124:127], v[136:139], v[188:191], v[124:127]
	v_mfma_f32_16x16x32_bf16 v[120:123], v[164:167], v[188:191], v[120:123]
	v_mfma_f32_16x16x32_bf16 v[116:119], v[136:139], v[196:199], v[116:119]
	v_mfma_f32_16x16x32_bf16 v[112:115], v[164:167], v[196:199], v[112:115]
	v_mfma_f32_16x16x32_bf16 v[108:111], v[136:139], v[204:207], v[108:111]
	v_mfma_f32_16x16x32_bf16 v[104:107], v[164:167], v[204:207], v[104:107]
	v_mfma_f32_16x16x32_bf16 v[100:103], v[136:139], v[212:215], v[100:103]
	v_mfma_f32_16x16x32_bf16 v[96:99], v[164:167], v[212:215], v[96:99]
	v_mfma_f32_16x16x32_bf16 v[124:127], v[140:143], v[192:195], v[124:127]
	v_mfma_f32_16x16x32_bf16 v[120:123], v[168:171], v[192:195], v[120:123]
	v_mfma_f32_16x16x32_bf16 v[116:119], v[140:143], v[200:203], v[116:119]
	v_mfma_f32_16x16x32_bf16 v[112:115], v[168:171], v[200:203], v[112:115]
	v_mfma_f32_16x16x32_bf16 v[108:111], v[140:143], v[208:211], v[108:111]
	v_mfma_f32_16x16x32_bf16 v[104:107], v[168:171], v[208:211], v[104:107]
	v_mfma_f32_16x16x32_bf16 v[100:103], v[140:143], v[216:219], v[100:103]
	v_mfma_f32_16x16x32_bf16 v[96:99], v[168:171], v[216:219], v[96:99]
	v_mfma_f32_16x16x32_bf16 v[60:63], v[172:175], v[188:191], v[60:63]
	v_mfma_f32_16x16x32_bf16 v[56:59], v[180:183], v[188:191], v[56:59]
	v_mfma_f32_16x16x32_bf16 v[52:55], v[172:175], v[196:199], v[52:55]
	v_mfma_f32_16x16x32_bf16 v[48:51], v[180:183], v[196:199], v[48:51]
	v_mfma_f32_16x16x32_bf16 v[44:47], v[172:175], v[204:207], v[44:47]
	v_mfma_f32_16x16x32_bf16 v[40:43], v[180:183], v[204:207], v[40:43]
	v_mfma_f32_16x16x32_bf16 v[36:39], v[172:175], v[212:215], v[36:39]
	v_mfma_f32_16x16x32_bf16 v[32:35], v[180:183], v[212:215], v[32:35]
	v_mfma_f32_16x16x32_bf16 v[60:63], v[176:179], v[192:195], v[60:63]
	v_mfma_f32_16x16x32_bf16 v[56:59], v[184:187], v[192:195], v[56:59]
	v_mfma_f32_16x16x32_bf16 v[52:55], v[176:179], v[200:203], v[52:55]
	v_mfma_f32_16x16x32_bf16 v[48:51], v[184:187], v[200:203], v[48:51]
	v_mfma_f32_16x16x32_bf16 v[44:47], v[176:179], v[208:211], v[44:47]
	v_mfma_f32_16x16x32_bf16 v[40:43], v[184:187], v[208:211], v[40:43]
	v_mfma_f32_16x16x32_bf16 v[36:39], v[176:179], v[216:219], v[36:39]
	v_mfma_f32_16x16x32_bf16 v[32:35], v[184:187], v[216:219], v[32:35]
	s_setprio 0
	s_barrier
	s_add_i32 s59, s53, s40
	v_lshl_add_u64 v[144:145], s[34:35], 0, v[156:157]
	s_mov_b32 m0, s59
	ds_read_b128 v[188:191], v151 offset:16384
	ds_read_b128 v[192:195], v151 offset:17408
	ds_read_b128 v[196:199], v151 offset:18432
	ds_read_b128 v[200:203], v151 offset:19456
	ds_read_b128 v[204:207], v151 offset:20480
	ds_read_b128 v[208:211], v151 offset:21504
	ds_read_b128 v[212:215], v151 offset:22528
	ds_read_b128 v[216:219], v151 offset:23552
	global_load_lds_dwordx4 v[144:145], off
	s_add_i32 m0, s59, 0x2000
	s_add_u32 s60, s34, 0x80000
	v_lshl_add_u64 v[220:221], s[34:35], 0, v[160:161]
	s_addc_u32 s61, s35, 0
	s_add_i32 s59, s54, s40
	global_load_lds_dwordx4 v[220:221], off
	v_lshl_add_u64 v[222:223], s[60:61], 0, v[156:157]
	s_mov_b32 m0, s59
	v_lshl_add_u64 v[224:225], s[36:37], 0, v[158:159]
	global_load_lds_dwordx4 v[222:223], off
	v_lshl_add_u64 v[222:223], s[60:61], 0, v[160:161]
	s_add_i32 m0, s59, 0x2000
	s_nop 0
	global_load_lds_dwordx4 v[222:223], off
	v_lshl_add_u64 v[222:223], s[36:37], 0, v[154:155]
	s_mov_b32 m0, s29
	s_nop 0
	global_load_lds_dwordx4 v[222:223], off
	s_mov_b32 m0, s41
	s_nop 0
	global_load_lds_dwordx4 v[224:225], off
	s_waitcnt vmcnt(8)
	s_waitcnt lgkmcnt(0)
	s_barrier
; #define PG8_STAGE(bufoff, gbase, voff) do { _Pragma("unroll") for (int _i = 0; _i < 2; ++_i) \
;         __builtin_amdgcn_global_load_lds((const unsigned*)((const char*)(gbase) + (voff)[_i]), (LAS unsigned*)(lds + (bufoff) + ldsw + _i * 8192), 16, 0, 0); } while (0)
; #define PG8_LDA(dst, b, h) do { _Pragma("unroll") for (int m = 0; m < 4; ++m) _Pragma("unroll") for (int k = 0; k < 2; ++k) dst[m][k] = *(const LAS bf16x8*)(lds + PG8_SA(b, h) + aoff + m * 2048 + k * 1024); } while (0)
; #define PG8_LDB(dst, b, h) do { _Pragma("unroll") for (int n = 0; n < 2; ++n) _Pragma("unroll") for (int k = 0; k < 2; ++k) dst[n][k] = *(const LAS bf16x8*)(lds + PG8_SB(b, h) + boff + n * 2048 + k * 1024); } while (0)
; #define PG8_MMA(ai, bj, At, Bt) do { __builtin_amdgcn_s_setprio(1); _Pragma("unroll") for (int m = 0; m < 4; ++m) _Pragma("unroll") for (int n = 0; n < 2; ++n) _Pragma("unroll") for (int k = 0; k < 2; ++k) \
;         acc[ai][bj][m][n] = __builtin_amdgcn_mfma_f32_16x16x32_bf16(Bt[n][k], At[m][k], acc[ai][bj][m][n], 0, 0, 0); __builtin_amdgcn_s_setprio(0); } while (0)
; #define PG8_WAIT_V(n) asm volatile("s_waitcnt vmcnt(" #n ")" ::: "memory")
; #define PG8_WAIT_L(n) asm volatile("s_waitcnt lgkmcnt(" #n ")" ::: "memory")
; #define PG8_BAR __builtin_amdgcn_s_barrier()
; #define PG8_SCHED __builtin_amdgcn_sched_barrier(0)
; template <class Epi, class Sched>
; __device__ __forceinline__ void gemm_phase(LAS unsigned char* lds, const Gemm g, const Sched& S, const Epi& E) {
;     ...
;             PG8_WAIT_V(8); PG8_WAIT_L(0); PG8_BAR; PG8_MMA(1, 0, At, B0); PG8_MMA(1, 1, At, B1); PG8_BAR; PG8_SCHED;
;             PG8_LDB(B0, 1, 0); PG8_LDB(B1, 1, 1); PG8_SCHED; PG8_LDA(At, 1, 0); PG8_STAGE(PG8_SA(0, 1), a2 + hstep, voffA);
;             PG8_WAIT_V(8); PG8_WAIT_L(0); PG8_BAR; PG8_MMA(0, 0, At, B0); PG8_MMA(0, 1, At, B1); PG8_BAR; PG8_SCHED;
	s_setprio 1
	s_waitcnt lgkmcnt(0)
	v_mfma_f32_16x16x32_bf16 v[92:95], v[136:139], v[188:191], v[92:95]
	v_mfma_f32_16x16x32_bf16 v[88:91], v[164:167], v[188:191], v[88:91]
	v_mfma_f32_16x16x32_bf16 v[84:87], v[136:139], v[196:199], v[84:87]
	v_mfma_f32_16x16x32_bf16 v[80:83], v[164:167], v[196:199], v[80:83]
	v_mfma_f32_16x16x32_bf16 v[76:79], v[136:139], v[204:207], v[76:79]
	v_mfma_f32_16x16x32_bf16 v[72:75], v[164:167], v[204:207], v[72:75]
	v_mfma_f32_16x16x32_bf16 v[68:71], v[136:139], v[212:215], v[68:71]
	v_mfma_f32_16x16x32_bf16 v[64:67], v[164:167], v[212:215], v[64:67]
	v_mfma_f32_16x16x32_bf16 v[92:95], v[140:143], v[192:195], v[92:95]
	v_mfma_f32_16x16x32_bf16 v[88:91], v[168:171], v[192:195], v[88:91]
	v_mfma_f32_16x16x32_bf16 v[84:87], v[140:143], v[200:203], v[84:87]
	v_mfma_f32_16x16x32_bf16 v[80:83], v[168:171], v[200:203], v[80:83]
	v_mfma_f32_16x16x32_bf16 v[76:79], v[140:143], v[208:211], v[76:79]
	v_mfma_f32_16x16x32_bf16 v[72:75], v[168:171], v[208:211], v[72:75]
	v_mfma_f32_16x16x32_bf16 v[68:71], v[140:143], v[216:219], v[68:71]
	v_mfma_f32_16x16x32_bf16 v[64:67], v[168:171], v[216:219], v[64:67]
	v_mfma_f32_16x16x32_bf16 v[28:31], v[172:175], v[188:191], v[28:31]
	v_mfma_f32_16x16x32_bf16 v[24:27], v[180:183], v[188:191], v[24:27]
	v_mfma_f32_16x16x32_bf16 v[20:23], v[172:175], v[196:199], v[20:23]
	v_mfma_f32_16x16x32_bf16 v[16:19], v[180:183], v[196:199], v[16:19]
	v_mfma_f32_16x16x32_bf16 v[12:15], v[172:175], v[204:207], v[12:15]
	v_mfma_f32_16x16x32_bf16 v[8:11], v[180:183], v[204:207], v[8:11]
	v_mfma_f32_16x16x32_bf16 v[4:7], v[172:175], v[212:215], v[4:7]
	v_mfma_f32_16x16x32_bf16 v[0:3], v[180:183], v[212:215], v[0:3]
	v_mfma_f32_16x16x32_bf16 v[28:31], v[176:179], v[192:195], v[28:31]
	v_mfma_f32_16x16x32_bf16 v[24:27], v[184:187], v[192:195], v[24:27]
	v_mfma_f32_16x16x32_bf16 v[20:23], v[176:179], v[200:203], v[20:23]
	v_mfma_f32_16x16x32_bf16 v[16:19], v[184:187], v[200:203], v[16:19]
	v_mfma_f32_16x16x32_bf16 v[12:15], v[176:179], v[208:211], v[12:15]
	v_mfma_f32_16x16x32_bf16 v[8:11], v[184:187], v[208:211], v[8:11]
	v_mfma_f32_16x16x32_bf16 v[4:7], v[176:179], v[216:219], v[4:7]
	v_mfma_f32_16x16x32_bf16 v[0:3], v[184:187], v[216:219], v[0:3]
	s_setprio 0
	s_barrier
	s_add_i32 s59, 0, 0x18000
	v_add_u32_e32 v153, s59, v147
	s_add_i32 s60, 0, 0x1c000
	ds_read_b128 v[136:139], v153
	ds_read_b128 v[140:143], v153 offset:1024
	ds_read_b128 v[164:167], v153 offset:2048
	ds_read_b128 v[168:171], v153 offset:3072
	v_add_u32_e32 v153, s60, v147
	ds_read_b128 v[172:175], v153
	ds_read_b128 v[176:179], v153 offset:1024
	ds_read_b128 v[180:183], v153 offset:2048
	ds_read_b128 v[184:187], v153 offset:3072
	s_add_u32 s36, s36, 0x80000
	s_addc_u32 s37, s37, 0
	s_mov_b32 m0, s42
	v_lshl_add_u64 v[226:227], s[36:37], 0, v[154:155]
	ds_read_b128 v[188:191], v151 offset:32768
	ds_read_b128 v[192:195], v151 offset:33792
	ds_read_b128 v[196:199], v151 offset:34816
	ds_read_b128 v[200:203], v151 offset:35840
	ds_read_b128 v[204:207], v151 offset:36864
	ds_read_b128 v[208:211], v151 offset:37888
	ds_read_b128 v[212:215], v151 offset:38912
	ds_read_b128 v[216:219], v151 offset:39936
	global_load_lds_dwordx4 v[226:227], off
	v_lshl_add_u64 v[226:227], s[36:37], 0, v[158:159]
	s_mov_b32 m0, s43
	s_nop 0
	global_load_lds_dwordx4 v[226:227], off
	s_waitcnt vmcnt(8)
	s_waitcnt lgkmcnt(0)
	s_barrier
	s_setprio 1
	s_waitcnt lgkmcnt(0)
	v_mfma_f32_16x16x32_bf16 v[124:127], v[136:139], v[188:191], v[124:127]
	v_mfma_f32_16x16x32_bf16 v[120:123], v[164:167], v[188:191], v[120:123]
	v_mfma_f32_16x16x32_bf16 v[116:119], v[136:139], v[196:199], v[116:119]
	v_mfma_f32_16x16x32_bf16 v[112:115], v[164:167], v[196:199], v[112:115]
	v_mfma_f32_16x16x32_bf16 v[108:111], v[136:139], v[204:207], v[108:111]
	v_mfma_f32_16x16x32_bf16 v[104:107], v[164:167], v[204:207], v[104:107]
	v_mfma_f32_16x16x32_bf16 v[100:103], v[136:139], v[212:215], v[100:103]
	v_mfma_f32_16x16x32_bf16 v[96:99], v[164:167], v[212:215], v[96:99]
	v_mfma_f32_16x16x32_bf16 v[124:127], v[140:143], v[192:195], v[124:127]
	v_mfma_f32_16x16x32_bf16 v[120:123], v[168:171], v[192:195], v[120:123]
	v_mfma_f32_16x16x32_bf16 v[116:119], v[140:143], v[200:203], v[116:119]
	v_mfma_f32_16x16x32_bf16 v[112:115], v[168:171], v[200:203], v[112:115]
	v_mfma_f32_16x16x32_bf16 v[108:111], v[140:143], v[208:211], v[108:111]
	v_mfma_f32_16x16x32_bf16 v[104:107], v[168:171], v[208:211], v[104:107]
	v_mfma_f32_16x16x32_bf16 v[100:103], v[140:143], v[216:219], v[100:103]
	v_mfma_f32_16x16x32_bf16 v[96:99], v[168:171], v[216:219], v[96:99]
	v_mfma_f32_16x16x32_bf16 v[60:63], v[172:175], v[188:191], v[60:63]
	v_mfma_f32_16x16x32_bf16 v[56:59], v[180:183], v[188:191], v[56:59]
	v_mfma_f32_16x16x32_bf16 v[52:55], v[172:175], v[196:199], v[52:55]
	v_mfma_f32_16x16x32_bf16 v[48:51], v[180:183], v[196:199], v[48:51]
	v_mfma_f32_16x16x32_bf16 v[44:47], v[172:175], v[204:207], v[44:47]
	v_mfma_f32_16x16x32_bf16 v[40:43], v[180:183], v[204:207], v[40:43]
	v_mfma_f32_16x16x32_bf16 v[36:39], v[172:175], v[212:215], v[36:39]
	v_mfma_f32_16x16x32_bf16 v[32:35], v[180:183], v[212:215], v[32:35]
	v_mfma_f32_16x16x32_bf16 v[60:63], v[176:179], v[192:195], v[60:63]
	v_mfma_f32_16x16x32_bf16 v[56:59], v[184:187], v[192:195], v[56:59]
	v_mfma_f32_16x16x32_bf16 v[52:55], v[176:179], v[200:203], v[52:55]
	v_mfma_f32_16x16x32_bf16 v[48:51], v[184:187], v[200:203], v[48:51]
	v_mfma_f32_16x16x32_bf16 v[44:47], v[176:179], v[208:211], v[44:47]
	v_mfma_f32_16x16x32_bf16 v[40:43], v[184:187], v[208:211], v[40:43]
	v_mfma_f32_16x16x32_bf16 v[36:39], v[176:179], v[216:219], v[36:39]
	v_mfma_f32_16x16x32_bf16 v[32:35], v[184:187], v[216:219], v[32:35]
	s_setprio 0
	s_barrier
; #define PG8_STAGE(bufoff, gbase, voff) do { _Pragma("unroll") for (int _i = 0; _i < 2; ++_i) \
;         __builtin_amdgcn_global_load_lds((const unsigned*)((const char*)(gbase) + (voff)[_i]), (LAS unsigned*)(lds + (bufoff) + ldsw + _i * 8192), 16, 0, 0); } while (0)
; #define PG8_LDA(dst, b, h) do { _Pragma("unroll") for (int m = 0; m < 4; ++m) _Pragma("unroll") for (int k = 0; k < 2; ++k) dst[m][k] = *(const LAS bf16x8*)(lds + PG8_SA(b, h) + aoff + m * 2048 + k * 1024); } while (0)
; #define PG8_MMA(ai, bj, At, Bt) do { __builtin_amdgcn_s_setprio(1); _Pragma("unroll") for (int m = 0; m < 4; ++m) _Pragma("unroll") for (int n = 0; n < 2; ++n) _Pragma("unroll") for (int k = 0; k < 2; ++k) \
;         acc[ai][bj][m][n] = __builtin_amdgcn_mfma_f32_16x16x32_bf16(Bt[n][k], At[m][k], acc[ai][bj][m][n], 0, 0, 0); __builtin_amdgcn_s_setprio(0); } while (0)
; #define PG8_WAIT_V(n) asm volatile("s_waitcnt vmcnt(" #n ")" ::: "memory")
; #define PG8_WAIT_L(n) asm volatile("s_waitcnt lgkmcnt(" #n ")" ::: "memory")
; #define PG8_BAR __builtin_amdgcn_s_barrier()
; #define PG8_SCHED __builtin_amdgcn_sched_barrier(0)
; template <class Epi, class Sched>
; __device__ __forceinline__ void gemm_phase(LAS unsigned char* lds, const Gemm g, const Sched& S, const Epi& E) {
;     ...
;             PG8_LDA(At, 1, 1); PG8_STAGE(PG8_SB(1, 0), b3, voffB); PG8_STAGE(PG8_SB(1, 1), b3 + hstep, voffB); PG8_STAGE(PG8_SA(1, 0), a3, voffA);
;             PG8_WAIT_V(8); PG8_WAIT_L(0); PG8_BAR; PG8_MMA(1, 0, At, B0); PG8_MMA(1, 1, At, B1); PG8_BAR; PG8_SCHED;
;         }
	s_add_i32 s36, s59, s40
	v_lshl_add_u64 v[144:145], v[144:145], 0, s[6:7]
	s_mov_b32 m0, s36
	ds_read_b128 v[188:191], v151 offset:49152
	ds_read_b128 v[192:195], v151 offset:50176
	ds_read_b128 v[196:199], v151 offset:51200
	ds_read_b128 v[200:203], v151 offset:52224
	ds_read_b128 v[204:207], v151 offset:53248
	ds_read_b128 v[208:211], v151 offset:54272
	ds_read_b128 v[212:215], v151 offset:55296
	ds_read_b128 v[216:219], v151 offset:56320
	global_load_lds_dwordx4 v[144:145], off
	s_add_i32 m0, s36, 0x2000
	s_add_u32 s34, s34, 0x80080
	v_lshl_add_u64 v[144:145], v[220:221], 0, s[6:7]
	s_addc_u32 s35, s35, 0
	s_add_i32 s36, s60, s40
	global_load_lds_dwordx4 v[144:145], off
	v_lshl_add_u64 v[144:145], s[34:35], 0, v[156:157]
	s_mov_b32 m0, s36
	s_nop 0
	global_load_lds_dwordx4 v[144:145], off
	v_lshl_add_u64 v[144:145], s[34:35], 0, v[160:161]
	s_add_i32 m0, s36, 0x2000
	s_nop 0
	global_load_lds_dwordx4 v[144:145], off
	v_lshl_add_u64 v[144:145], v[222:223], 0, s[6:7]
	s_mov_b32 m0, s47
	s_nop 0
	global_load_lds_dwordx4 v[144:145], off
	v_lshl_add_u64 v[144:145], v[224:225], 0, s[6:7]
	s_mov_b32 m0, s48
	s_nop 0
	global_load_lds_dwordx4 v[144:145], off
	s_waitcnt vmcnt(8)
	s_waitcnt lgkmcnt(0)
	s_barrier
	s_setprio 1
	s_waitcnt lgkmcnt(0)
	v_mfma_f32_16x16x32_bf16 v[92:95], v[136:139], v[188:191], v[92:95]
	v_mfma_f32_16x16x32_bf16 v[88:91], v[164:167], v[188:191], v[88:91]
	v_mfma_f32_16x16x32_bf16 v[84:87], v[136:139], v[196:199], v[84:87]
	v_mfma_f32_16x16x32_bf16 v[80:83], v[164:167], v[196:199], v[80:83]
	v_mfma_f32_16x16x32_bf16 v[76:79], v[136:139], v[204:207], v[76:79]
	v_mfma_f32_16x16x32_bf16 v[72:75], v[164:167], v[204:207], v[72:75]
	v_mfma_f32_16x16x32_bf16 v[68:71], v[136:139], v[212:215], v[68:71]
	v_mfma_f32_16x16x32_bf16 v[64:67], v[164:167], v[212:215], v[64:67]
	v_mfma_f32_16x16x32_bf16 v[92:95], v[140:143], v[192:195], v[92:95]
	v_mfma_f32_16x16x32_bf16 v[88:91], v[168:171], v[192:195], v[88:91]
	v_mfma_f32_16x16x32_bf16 v[84:87], v[140:143], v[200:203], v[84:87]
	v_mfma_f32_16x16x32_bf16 v[80:83], v[168:171], v[200:203], v[80:83]
	v_mfma_f32_16x16x32_bf16 v[76:79], v[140:143], v[208:211], v[76:79]
	v_mfma_f32_16x16x32_bf16 v[72:75], v[168:171], v[208:211], v[72:75]
	v_mfma_f32_16x16x32_bf16 v[68:71], v[140:143], v[216:219], v[68:71]
	v_mfma_f32_16x16x32_bf16 v[64:67], v[168:171], v[216:219], v[64:67]
	v_mfma_f32_16x16x32_bf16 v[28:31], v[172:175], v[188:191], v[28:31]
	v_mfma_f32_16x16x32_bf16 v[24:27], v[180:183], v[188:191], v[24:27]
	v_mfma_f32_16x16x32_bf16 v[20:23], v[172:175], v[196:199], v[20:23]
	v_mfma_f32_16x16x32_bf16 v[16:19], v[180:183], v[196:199], v[16:19]
	v_mfma_f32_16x16x32_bf16 v[12:15], v[172:175], v[204:207], v[12:15]
	v_mfma_f32_16x16x32_bf16 v[8:11], v[180:183], v[204:207], v[8:11]
	v_mfma_f32_16x16x32_bf16 v[4:7], v[172:175], v[212:215], v[4:7]
	v_mfma_f32_16x16x32_bf16 v[0:3], v[180:183], v[212:215], v[0:3]
	v_mfma_f32_16x16x32_bf16 v[28:31], v[176:179], v[192:195], v[28:31]
	v_mfma_f32_16x16x32_bf16 v[24:27], v[184:187], v[192:195], v[24:27]
	v_mfma_f32_16x16x32_bf16 v[20:23], v[176:179], v[200:203], v[20:23]
	v_mfma_f32_16x16x32_bf16 v[16:19], v[184:187], v[200:203], v[16:19]
	v_mfma_f32_16x16x32_bf16 v[12:15], v[176:179], v[208:211], v[12:15]
	v_mfma_f32_16x16x32_bf16 v[8:11], v[184:187], v[208:211], v[8:11]
	v_mfma_f32_16x16x32_bf16 v[4:7], v[176:179], v[216:219], v[4:7]
	v_mfma_f32_16x16x32_bf16 v[0:3], v[184:187], v[216:219], v[0:3]
	s_setprio 0
	s_barrier
	s_add_i32 s58, s58, 2
	s_add_u32 s30, s30, 0x100
	s_addc_u32 s31, s31, 0
	s_add_u32 s33, s33, 0x100
	s_addc_u32 s55, s55, 0
	s_cmp_gt_u32 s58, 29
	s_cbranch_scc0 .LBB0_939
	s_and_b64 vcc, exec, s[8:9]
	s_cbranch_vccz .LBB0_942
	s_barrier
